# K-loop: 30 duplicate already-satisfied lgkmcnt(0) waits at MFMA segment heads removed, on top of hoisted scalar-base version
# speedup vs baseline: 1.0106x; 1.0106x over previous
;     __device__ __forceinline__ void prefetch(const Unit& u, int wr, int wc, int lane) const { lnfold_prefetch(vl, stats, gW, bW, u, wr, wc, lane); }
;     __device__ __forceinline__ void prefetch(const Unit& u, int wr, int wc, int lane) const { lnfold_prefetch(vl, stats, gW, bW, u, wr, wc, lane); }
; #define PG8_STAGE(bufoff, gbase, voff) do { _Pragma("unroll") for (int _i = 0; _i < 2; ++_i) \
;         __builtin_amdgcn_global_load_lds((const unsigned*)((const char*)(gbase) + (voff)[_i]), (LAS unsigned*)(lds + (bufoff) + ldsw + _i * 8192), 16, 0, 0); } while (0)
; #define PG8_LDA(dst, b, h) do { _Pragma("unroll") for (int m = 0; m < 4; ++m) _Pragma("unroll") for (int k = 0; k < 2; ++k) dst[m][k] = *(const LAS f16x8*)(lds + PG8_SA(b, h) + aoff + m * 2048 + k * 1024); } while (0)
; #define PG8_LDB(dst, b, h) do { _Pragma("unroll") for (int n = 0; n < 2; ++n) _Pragma("unroll") for (int k = 0; k < 2; ++k) dst[n][k] = *(const LAS f16x8*)(lds + PG8_SB(b, h) + boff + n * 2048 + k * 1024); } while (0)
; #define PG8_WAIT_V(n) asm volatile("s_waitcnt vmcnt(" #n ")" ::: "memory")
; #define PG8_WAIT_L(n) asm volatile("s_waitcnt lgkmcnt(" #n ")" ::: "memory")
; template <class Epi>
; __device__ __forceinline__ void gemm_phase(LAS unsigned char* lds, const Gemm g0, const StaticOrder& S, const Epi& E) {
;     ...
;         for (int t = 0; t < nt; t += 2) {
;             const bool last = (t == nt - 2);
;             if (Epi::PREF && last) E.prefetch(cur, wr, wc, lane);
;             const char* a1 = cA + (size_t)(t + 1) * kstep;
;             const char* a2 = last ? nA : cA + (size_t)(t + 2) * kstep; const char* b2 = last ? nB : cB + (size_t)(t + 2) * kstep;
;             const char* a3 = a2 + kstep; const char* b3 = b2 + kstep;
;             PG8_LDB(B0, 0, 0); PG8_SCHED; PG8_LDA(At, 0, 0); PG8_STAGE(PG8_SA(1, 1), a1 + hstep, voffA);
;             PG8_WAIT_L(8); PG8_BAR; PG8_WAIT_L(0); PG8_MMA(0, 0, At, B0); PG8_BAR; PG8_SCHED;
;             PG8_LDB(B1, 0, 1); PG8_STAGE(PG8_SB(0, 0), b2, voffB);
;             PG8_BAR; PG8_WAIT_L(0); PG8_MMA(0, 1, At, B1); PG8_BAR;
;             PG8_LDA(At, 0, 1); PG8_STAGE(PG8_SA(0, 0), a2, voffA);
;             PG8_BAR; PG8_WAIT_L(0); PG8_MMA(1, 0, At, B0); PG8_BAR; PG8_SCHED;
;             PG8_STAGE(PG8_SB(0, 1), b2 + hstep, voffB);
;             PG8_WAIT_V(6); PG8_BAR; PG8_MMA(1, 1, At, B1); PG8_BAR;
.LBB0_198:
	s_add_u32 s52, s0, 0xfff80080
	s_addc_u32 s53, s1, -1
	s_and_b64 s[22:23], s[50:51], exec
	s_cselect_b32 s53, s75, s53
	s_cselect_b32 s52, s80, s52
	s_add_i32 s84, 0, 0x10000
	ds_read_b128 v[136:139], v161
	ds_read_b128 v[140:143], v161 offset:1024
	ds_read_b128 v[144:147], v161 offset:2048
	ds_read_b128 v[148:151], v161 offset:3072
	s_and_b64 s[22:23], s[50:51], exec
	s_cselect_b32 s51, s81, s25
	s_cselect_b32 s50, s82, s24
	s_add_i32 m0, s28, 0xc000
	ds_read_b128 v[152:155], v222
	ds_read_b128 v[156:159], v222 offset:1024
	ds_read_b128 v[186:189], v222 offset:2048
	ds_read_b128 v[190:193], v222 offset:3072
	ds_read_b128 v[194:197], v222 offset:4096
	ds_read_b128 v[198:201], v222 offset:5120
	ds_read_b128 v[202:205], v222 offset:6144
	ds_read_b128 v[206:209], v222 offset:7168
	global_load_lds_dwordx4 v184, s[0:1]
	s_add_i32 m0, s28, 0xe000
	s_nop 0
	global_load_lds_dwordx4 v182, s[0:1]
	s_waitcnt lgkmcnt(8)
	s_barrier
	s_waitcnt lgkmcnt(0)
	v_mfma_f32_16x16x32_f16 v[126:129], v[136:139], v[152:155], v[126:129]
	v_mfma_f32_16x16x32_f16 v[122:125], v[144:147], v[152:155], v[122:125]
	v_mfma_f32_16x16x32_f16 v[118:121], v[136:139], v[186:189], v[118:121]
	v_mfma_f32_16x16x32_f16 v[110:113], v[144:147], v[186:189], v[110:113]
	v_mfma_f32_16x16x32_f16 v[102:105], v[136:139], v[194:197], v[102:105]
	v_mfma_f32_16x16x32_f16 v[98:101], v[144:147], v[194:197], v[98:101]
	v_mfma_f32_16x16x32_f16 v[86:89], v[136:139], v[202:205], v[86:89]
	v_mfma_f32_16x16x32_f16 v[82:85], v[144:147], v[202:205], v[82:85]
	v_mfma_f32_16x16x32_f16 v[126:129], v[140:143], v[156:159], v[126:129]
	v_mfma_f32_16x16x32_f16 v[122:125], v[148:151], v[156:159], v[122:125]
	v_mfma_f32_16x16x32_f16 v[118:121], v[140:143], v[190:193], v[118:121]
	v_mfma_f32_16x16x32_f16 v[110:113], v[148:151], v[190:193], v[110:113]
	v_mfma_f32_16x16x32_f16 v[102:105], v[140:143], v[198:201], v[102:105]
	v_mfma_f32_16x16x32_f16 v[98:101], v[148:151], v[198:201], v[98:101]
	v_mfma_f32_16x16x32_f16 v[86:89], v[140:143], v[206:209], v[86:89]
	v_mfma_f32_16x16x32_f16 v[82:85], v[148:151], v[206:209], v[82:85]
	s_barrier
	s_add_i32 s85, 0, 0x14000
	s_add_i32 s22, s84, s19
	ds_read_b128 v[210:213], v161 offset:16384
	ds_read_b128 v[234:237], v161 offset:17408
	ds_read_b128 v[238:241], v161 offset:18432
	s_mov_b32 m0, s22
	ds_read_b128 v[242:245], v161 offset:19456
	global_load_lds_dwordx4 v178, s[50:51]
	s_add_i32 m0, s22, 0x2000
	s_nop 0
	global_load_lds_dwordx4 v174, s[50:51]
	s_barrier
	s_waitcnt lgkmcnt(0)
	v_mfma_f32_16x16x32_f16 v[114:117], v[210:213], v[152:155], v[114:117]
	v_mfma_f32_16x16x32_f16 v[106:109], v[238:241], v[152:155], v[106:109]
	v_mfma_f32_16x16x32_f16 v[94:97], v[210:213], v[186:189], v[94:97]
	v_mfma_f32_16x16x32_f16 v[90:93], v[238:241], v[186:189], v[90:93]
	v_mfma_f32_16x16x32_f16 v[78:81], v[210:213], v[194:197], v[78:81]
	v_mfma_f32_16x16x32_f16 v[74:77], v[238:241], v[194:197], v[74:77]
	v_mfma_f32_16x16x32_f16 v[70:73], v[210:213], v[202:205], v[70:73]
	v_mfma_f32_16x16x32_f16 v[66:69], v[238:241], v[202:205], v[66:69]
	v_mfma_f32_16x16x32_f16 v[114:117], v[234:237], v[156:159], v[114:117]
	v_mfma_f32_16x16x32_f16 v[106:109], v[242:245], v[156:159], v[106:109]
	v_mfma_f32_16x16x32_f16 v[94:97], v[234:237], v[190:193], v[94:97]
	v_mfma_f32_16x16x32_f16 v[90:93], v[242:245], v[190:193], v[90:93]
	v_mfma_f32_16x16x32_f16 v[78:81], v[234:237], v[198:201], v[78:81]
	v_mfma_f32_16x16x32_f16 v[74:77], v[242:245], v[198:201], v[74:77]
	v_mfma_f32_16x16x32_f16 v[70:73], v[234:237], v[206:209], v[70:73]
	v_mfma_f32_16x16x32_f16 v[66:69], v[242:245], v[206:209], v[66:69]
	s_mov_b32 m0, s28
	s_barrier
	ds_read_b128 v[152:155], v222 offset:16384
	ds_read_b128 v[156:159], v222 offset:17408
	ds_read_b128 v[186:189], v222 offset:18432
	ds_read_b128 v[190:193], v222 offset:19456
	ds_read_b128 v[194:197], v222 offset:20480
	ds_read_b128 v[198:201], v222 offset:21504
	ds_read_b128 v[202:205], v222 offset:22528
	ds_read_b128 v[206:209], v222 offset:23552
	global_load_lds_dwordx4 v180, s[52:53]
	s_mov_b32 m0, s29
	s_nop 0
	global_load_lds_dwordx4 v176, s[52:53]
	s_barrier
	s_waitcnt lgkmcnt(0)
	v_mfma_f32_16x16x32_f16 v[62:65], v[136:139], v[152:155], v[62:65]
	v_mfma_f32_16x16x32_f16 v[58:61], v[144:147], v[152:155], v[58:61]
	v_mfma_f32_16x16x32_f16 v[54:57], v[136:139], v[186:189], v[54:57]
	v_mfma_f32_16x16x32_f16 v[50:53], v[144:147], v[186:189], v[50:53]
	v_mfma_f32_16x16x32_f16 v[38:41], v[136:139], v[194:197], v[38:41]
	v_mfma_f32_16x16x32_f16 v[30:33], v[144:147], v[194:197], v[30:33]
	v_mfma_f32_16x16x32_f16 v[22:25], v[136:139], v[202:205], v[22:25]
	v_mfma_f32_16x16x32_f16 v[18:21], v[144:147], v[202:205], v[18:21]
	v_mfma_f32_16x16x32_f16 v[62:65], v[140:143], v[156:159], v[62:65]
	v_mfma_f32_16x16x32_f16 v[58:61], v[148:151], v[156:159], v[58:61]
	v_mfma_f32_16x16x32_f16 v[54:57], v[140:143], v[190:193], v[54:57]
	v_mfma_f32_16x16x32_f16 v[50:53], v[148:151], v[190:193], v[50:53]
	v_mfma_f32_16x16x32_f16 v[38:41], v[140:143], v[198:201], v[38:41]
	v_mfma_f32_16x16x32_f16 v[30:33], v[148:151], v[198:201], v[30:33]
	v_mfma_f32_16x16x32_f16 v[22:25], v[140:143], v[206:209], v[22:25]
	v_mfma_f32_16x16x32_f16 v[18:21], v[148:151], v[206:209], v[18:21]
	s_barrier
	s_add_u32 s22, s50, 0x80000
	s_addc_u32 s23, s51, 0
	s_add_i32 s84, s85, s19
	s_mov_b32 m0, s84
	s_nop 0
	global_load_lds_dwordx4 v178, s[22:23]
	s_add_i32 m0, s84, 0x2000
	s_nop 0
	global_load_lds_dwordx4 v174, s[22:23]
	s_waitcnt vmcnt(6)
	s_barrier
; #define PG8_STAGE(bufoff, gbase, voff) do { _Pragma("unroll") for (int _i = 0; _i < 2; ++_i) \
;         __builtin_amdgcn_global_load_lds((const unsigned*)((const char*)(gbase) + (voff)[_i]), (LAS unsigned*)(lds + (bufoff) + ldsw + _i * 8192), 16, 0, 0); } while (0)
; #define PG8_LDA(dst, b, h) do { _Pragma("unroll") for (int m = 0; m < 4; ++m) _Pragma("unroll") for (int k = 0; k < 2; ++k) dst[m][k] = *(const LAS f16x8*)(lds + PG8_SA(b, h) + aoff + m * 2048 + k * 1024); } while (0)
; #define PG8_LDB(dst, b, h) do { _Pragma("unroll") for (int n = 0; n < 2; ++n) _Pragma("unroll") for (int k = 0; k < 2; ++k) dst[n][k] = *(const LAS f16x8*)(lds + PG8_SB(b, h) + boff + n * 2048 + k * 1024); } while (0)
; #define PG8_MMA(ai, bj, At, Bt) do { __builtin_amdgcn_s_setprio(1); _Pragma("unroll") for (int m = 0; m < 4; ++m) _Pragma("unroll") for (int n = 0; n < 2; ++n) _Pragma("unroll") for (int k = 0; k < 2; ++k) \
;         acc[ai][bj][m][n] = __builtin_amdgcn_mfma_f32_16x16x32_f16(Bt[n][k], At[m][k], acc[ai][bj][m][n], 0, 0, 0); __builtin_amdgcn_s_setprio(0); } while (0)
; #define PG8_WAIT_V(n) asm volatile("s_waitcnt vmcnt(" #n ")" ::: "memory")
; #define PG8_WAIT_L(n) asm volatile("s_waitcnt lgkmcnt(" #n ")" ::: "memory")
; #define PG8_BAR __builtin_amdgcn_s_barrier()
; #define PG8_SCHED __builtin_amdgcn_sched_barrier(0)
; template <class Epi>
; __device__ __forceinline__ void gemm_phase(LAS unsigned char* lds, const Gemm g0, const StaticOrder& S, const Epi& E) {
;     ...
;             PG8_WAIT_V(6); PG8_BAR; PG8_MMA(1, 1, At, B1); PG8_BAR;
;             PG8_LDB(B0, 1, 0); PG8_SCHED; PG8_LDA(At, 1, 0); PG8_STAGE(PG8_SA(0, 1), a2 + hstep, voffA);
;             PG8_WAIT_L(8); PG8_BAR; PG8_WAIT_L(0); PG8_MMA(0, 0, At, B0); PG8_BAR; PG8_SCHED;
;             PG8_LDB(B1, 1, 1); PG8_STAGE(PG8_SB(1, 0), b3, voffB);
;             PG8_BAR; PG8_WAIT_L(0); PG8_MMA(0, 1, At, B1); PG8_BAR;
	v_mfma_f32_16x16x32_f16 v[46:49], v[210:213], v[152:155], v[46:49]
	v_mfma_f32_16x16x32_f16 v[42:45], v[238:241], v[152:155], v[42:45]
	v_mfma_f32_16x16x32_f16 v[34:37], v[210:213], v[186:189], v[34:37]
	v_mfma_f32_16x16x32_f16 v[26:29], v[238:241], v[186:189], v[26:29]
	v_mfma_f32_16x16x32_f16 v[14:17], v[210:213], v[194:197], v[14:17]
	v_mfma_f32_16x16x32_f16 v[10:13], v[238:241], v[194:197], v[10:13]
	v_mfma_f32_16x16x32_f16 v[6:9], v[210:213], v[202:205], v[6:9]
	v_mfma_f32_16x16x32_f16 v[2:5], v[238:241], v[202:205], v[2:5]
	v_mfma_f32_16x16x32_f16 v[46:49], v[234:237], v[156:159], v[46:49]
	v_mfma_f32_16x16x32_f16 v[42:45], v[242:245], v[156:159], v[42:45]
	v_mfma_f32_16x16x32_f16 v[34:37], v[234:237], v[190:193], v[34:37]
	v_mfma_f32_16x16x32_f16 v[26:29], v[242:245], v[190:193], v[26:29]
	v_mfma_f32_16x16x32_f16 v[14:17], v[234:237], v[198:201], v[14:17]
	v_mfma_f32_16x16x32_f16 v[10:13], v[242:245], v[198:201], v[10:13]
	v_mfma_f32_16x16x32_f16 v[6:9], v[234:237], v[206:209], v[6:9]
	v_mfma_f32_16x16x32_f16 v[2:5], v[242:245], v[206:209], v[2:5]
	s_add_i32 s84, 0, 0x18000
	s_barrier
	ds_read_b128 v[136:139], v161 offset:32768
	ds_read_b128 v[140:143], v161 offset:33792
	ds_read_b128 v[144:147], v161 offset:34816
	ds_read_b128 v[148:151], v161 offset:35840
	s_add_u32 s22, s52, 0x80000
	s_addc_u32 s23, s53, 0
	s_mov_b32 m0, s31
	ds_read_b128 v[152:155], v222 offset:32768
	ds_read_b128 v[156:159], v222 offset:33792
	ds_read_b128 v[186:189], v222 offset:34816
	ds_read_b128 v[190:193], v222 offset:35840
	ds_read_b128 v[194:197], v222 offset:36864
	ds_read_b128 v[198:201], v222 offset:37888
	ds_read_b128 v[202:205], v222 offset:38912
	ds_read_b128 v[206:209], v222 offset:39936
	global_load_lds_dwordx4 v180, s[22:23]
	s_mov_b32 m0, s58
	s_nop 0
	global_load_lds_dwordx4 v176, s[22:23]
	s_waitcnt lgkmcnt(8)
	s_barrier
	s_waitcnt lgkmcnt(0)
	v_mfma_f32_16x16x32_f16 v[126:129], v[136:139], v[152:155], v[126:129]
	v_mfma_f32_16x16x32_f16 v[122:125], v[144:147], v[152:155], v[122:125]
	v_mfma_f32_16x16x32_f16 v[118:121], v[136:139], v[186:189], v[118:121]
	v_mfma_f32_16x16x32_f16 v[110:113], v[144:147], v[186:189], v[110:113]
	v_mfma_f32_16x16x32_f16 v[102:105], v[136:139], v[194:197], v[102:105]
	v_mfma_f32_16x16x32_f16 v[98:101], v[144:147], v[194:197], v[98:101]
	v_mfma_f32_16x16x32_f16 v[86:89], v[136:139], v[202:205], v[86:89]
	v_mfma_f32_16x16x32_f16 v[82:85], v[144:147], v[202:205], v[82:85]
	v_mfma_f32_16x16x32_f16 v[126:129], v[140:143], v[156:159], v[126:129]
	v_mfma_f32_16x16x32_f16 v[122:125], v[148:151], v[156:159], v[122:125]
	v_mfma_f32_16x16x32_f16 v[118:121], v[140:143], v[190:193], v[118:121]
	v_mfma_f32_16x16x32_f16 v[110:113], v[148:151], v[190:193], v[110:113]
	v_mfma_f32_16x16x32_f16 v[102:105], v[140:143], v[198:201], v[102:105]
	v_mfma_f32_16x16x32_f16 v[98:101], v[148:151], v[198:201], v[98:101]
	v_mfma_f32_16x16x32_f16 v[86:89], v[140:143], v[206:209], v[86:89]
	v_mfma_f32_16x16x32_f16 v[82:85], v[148:151], v[206:209], v[82:85]
	s_barrier
	s_add_i32 s85, 0, 0x1c000
	s_add_i32 s22, s84, s19
	s_mov_b32 m0, s22
	ds_read_b128 v[210:213], v161 offset:49152
	ds_read_b128 v[234:237], v161 offset:50176
	ds_read_b128 v[238:241], v161 offset:51200
	ds_read_b128 v[242:245], v161 offset:52224
	global_load_lds_dwordx4 v160, s[50:51]
	s_add_i32 m0, s22, 0x2000
	s_nop 0
	global_load_lds_dwordx4 v162, s[50:51]
	s_barrier
; #define PG8_STAGE(bufoff, gbase, voff) do { _Pragma("unroll") for (int _i = 0; _i < 2; ++_i) \
;         __builtin_amdgcn_global_load_lds((const unsigned*)((const char*)(gbase) + (voff)[_i]), (LAS unsigned*)(lds + (bufoff) + ldsw + _i * 8192), 16, 0, 0); } while (0)
; #define PG8_LDA(dst, b, h) do { _Pragma("unroll") for (int m = 0; m < 4; ++m) _Pragma("unroll") for (int k = 0; k < 2; ++k) dst[m][k] = *(const LAS f16x8*)(lds + PG8_SA(b, h) + aoff + m * 2048 + k * 1024); } while (0)
; #define PG8_MMA(ai, bj, At, Bt) do { __builtin_amdgcn_s_setprio(1); _Pragma("unroll") for (int m = 0; m < 4; ++m) _Pragma("unroll") for (int n = 0; n < 2; ++n) _Pragma("unroll") for (int k = 0; k < 2; ++k) \
;         acc[ai][bj][m][n] = __builtin_amdgcn_mfma_f32_16x16x32_f16(Bt[n][k], At[m][k], acc[ai][bj][m][n], 0, 0, 0); __builtin_amdgcn_s_setprio(0); } while (0)
; #define PG8_WAIT_V(n) asm volatile("s_waitcnt vmcnt(" #n ")" ::: "memory")
; #define PG8_WAIT_L(n) asm volatile("s_waitcnt lgkmcnt(" #n ")" ::: "memory")
; #define PG8_BAR __builtin_amdgcn_s_barrier()
; #define PG8_SCHED __builtin_amdgcn_sched_barrier(0)
; template <class Epi>
; __device__ __forceinline__ void gemm_phase(LAS unsigned char* lds, const Gemm g0, const StaticOrder& S, const Epi& E) {
;     ...
;             PG8_BAR; PG8_WAIT_L(0); PG8_MMA(0, 1, At, B1); PG8_BAR;
;             PG8_LDA(At, 1, 1); PG8_STAGE(PG8_SA(1, 0), a3, voffA);
;             PG8_BAR; PG8_WAIT_L(0); PG8_MMA(1, 0, At, B0); PG8_BAR; PG8_SCHED;
;             PG8_STAGE(PG8_SB(1, 1), b3 + hstep, voffB);
;             PG8_WAIT_V(6); PG8_BAR; PG8_MMA(1, 1, At, B1); PG8_BAR;
;         }
	s_waitcnt lgkmcnt(0)
	v_mfma_f32_16x16x32_f16 v[114:117], v[210:213], v[152:155], v[114:117]
	v_mfma_f32_16x16x32_f16 v[106:109], v[238:241], v[152:155], v[106:109]
	v_mfma_f32_16x16x32_f16 v[94:97], v[210:213], v[186:189], v[94:97]
	v_mfma_f32_16x16x32_f16 v[90:93], v[238:241], v[186:189], v[90:93]
	v_mfma_f32_16x16x32_f16 v[78:81], v[210:213], v[194:197], v[78:81]
	v_mfma_f32_16x16x32_f16 v[74:77], v[238:241], v[194:197], v[74:77]
	v_mfma_f32_16x16x32_f16 v[70:73], v[210:213], v[202:205], v[70:73]
	v_mfma_f32_16x16x32_f16 v[66:69], v[238:241], v[202:205], v[66:69]
	v_mfma_f32_16x16x32_f16 v[114:117], v[234:237], v[156:159], v[114:117]
	v_mfma_f32_16x16x32_f16 v[106:109], v[242:245], v[156:159], v[106:109]
	v_mfma_f32_16x16x32_f16 v[94:97], v[234:237], v[190:193], v[94:97]
	v_mfma_f32_16x16x32_f16 v[90:93], v[242:245], v[190:193], v[90:93]
	v_mfma_f32_16x16x32_f16 v[78:81], v[234:237], v[198:201], v[78:81]
	v_mfma_f32_16x16x32_f16 v[74:77], v[242:245], v[198:201], v[74:77]
	v_mfma_f32_16x16x32_f16 v[70:73], v[234:237], v[206:209], v[70:73]
	v_mfma_f32_16x16x32_f16 v[66:69], v[242:245], v[206:209], v[66:69]
	s_mov_b32 m0, s59
	s_barrier
	ds_read_b128 v[152:155], v222 offset:49152
	ds_read_b128 v[156:159], v222 offset:50176
	ds_read_b128 v[186:189], v222 offset:51200
	ds_read_b128 v[190:193], v222 offset:52224
	ds_read_b128 v[194:197], v222 offset:53248
	ds_read_b128 v[198:201], v222 offset:54272
	ds_read_b128 v[202:205], v222 offset:55296
	ds_read_b128 v[206:209], v222 offset:56320
	global_load_lds_dwordx4 v164, s[52:53]
	s_mov_b32 m0, s61
	s_nop 0
	global_load_lds_dwordx4 v170, s[52:53]
	s_barrier
	s_waitcnt lgkmcnt(0)
	v_mfma_f32_16x16x32_f16 v[62:65], v[136:139], v[152:155], v[62:65]
	v_mfma_f32_16x16x32_f16 v[58:61], v[144:147], v[152:155], v[58:61]
	v_mfma_f32_16x16x32_f16 v[54:57], v[136:139], v[186:189], v[54:57]
	v_mfma_f32_16x16x32_f16 v[50:53], v[144:147], v[186:189], v[50:53]
	v_mfma_f32_16x16x32_f16 v[38:41], v[136:139], v[194:197], v[38:41]
	v_mfma_f32_16x16x32_f16 v[30:33], v[144:147], v[194:197], v[30:33]
	v_mfma_f32_16x16x32_f16 v[22:25], v[136:139], v[202:205], v[22:25]
	v_mfma_f32_16x16x32_f16 v[18:21], v[144:147], v[202:205], v[18:21]
	v_mfma_f32_16x16x32_f16 v[62:65], v[140:143], v[156:159], v[62:65]
	v_mfma_f32_16x16x32_f16 v[58:61], v[148:151], v[156:159], v[58:61]
	v_mfma_f32_16x16x32_f16 v[54:57], v[140:143], v[190:193], v[54:57]
	v_mfma_f32_16x16x32_f16 v[50:53], v[148:151], v[190:193], v[50:53]
	v_mfma_f32_16x16x32_f16 v[38:41], v[140:143], v[198:201], v[38:41]
	v_mfma_f32_16x16x32_f16 v[30:33], v[148:151], v[198:201], v[30:33]
	v_mfma_f32_16x16x32_f16 v[22:25], v[140:143], v[206:209], v[22:25]
	v_mfma_f32_16x16x32_f16 v[18:21], v[148:151], v[206:209], v[18:21]
	s_barrier
	s_add_u32 s22, s50, 0x80080
	s_addc_u32 s23, s51, 0
	s_add_i32 s50, s85, s19
	s_mov_b32 m0, s50
	s_nop 0
	global_load_lds_dwordx4 v178, s[22:23]
	s_add_i32 m0, s50, 0x2000
	s_nop 0
	global_load_lds_dwordx4 v174, s[22:23]
	s_waitcnt vmcnt(6)
	s_barrier
	v_mfma_f32_16x16x32_f16 v[46:49], v[210:213], v[152:155], v[46:49]
	v_mfma_f32_16x16x32_f16 v[42:45], v[238:241], v[152:155], v[42:45]
	v_mfma_f32_16x16x32_f16 v[34:37], v[210:213], v[186:189], v[34:37]
	v_mfma_f32_16x16x32_f16 v[26:29], v[238:241], v[186:189], v[26:29]
	v_mfma_f32_16x16x32_f16 v[14:17], v[210:213], v[194:197], v[14:17]
	v_mfma_f32_16x16x32_f16 v[10:13], v[238:241], v[194:197], v[10:13]
	v_mfma_f32_16x16x32_f16 v[6:9], v[210:213], v[202:205], v[6:9]
	v_mfma_f32_16x16x32_f16 v[2:5], v[238:241], v[202:205], v[2:5]
	v_mfma_f32_16x16x32_f16 v[46:49], v[234:237], v[156:159], v[46:49]
	v_mfma_f32_16x16x32_f16 v[42:45], v[242:245], v[156:159], v[42:45]
	v_mfma_f32_16x16x32_f16 v[34:37], v[234:237], v[190:193], v[34:37]
	v_mfma_f32_16x16x32_f16 v[26:29], v[242:245], v[190:193], v[26:29]
	v_mfma_f32_16x16x32_f16 v[14:17], v[234:237], v[198:201], v[14:17]
	v_mfma_f32_16x16x32_f16 v[10:13], v[242:245], v[198:201], v[10:13]
	v_mfma_f32_16x16x32_f16 v[6:9], v[234:237], v[206:209], v[6:9]
	v_mfma_f32_16x16x32_f16 v[2:5], v[242:245], v[206:209], v[2:5]
	s_add_i32 s83, s83, 2
	s_add_u32 s24, s24, 0x100
	s_addc_u32 s25, s25, 0
	s_add_u32 s0, s0, 0x100
	s_addc_u32 s1, s1, 0
	s_cmp_gt_u32 s83, 29
	s_barrier
	s_cbranch_scc1 .LBB0_201

;     __device__ __forceinline__ void prefetch(const Unit& u, int wr, int wc, int lane) const { lnfold_prefetch(vl, stats, gW, bW, u, wr, wc, lane); }
;     __device__ __forceinline__ void prefetch(const Unit& u, int wr, int wc, int lane) const { lnfold_prefetch(vl, stats, gW, bW, u, wr, wc, lane); }
; #define PG8_STAGE(bufoff, gbase, voff) do { _Pragma("unroll") for (int _i = 0; _i < 2; ++_i) \
;         __builtin_amdgcn_global_load_lds((const unsigned*)((const char*)(gbase) + (voff)[_i]), (LAS unsigned*)(lds + (bufoff) + ldsw + _i * 8192), 16, 0, 0); } while (0)
; #define PG8_LDA(dst, b, h) do { _Pragma("unroll") for (int m = 0; m < 4; ++m) _Pragma("unroll") for (int k = 0; k < 2; ++k) dst[m][k] = *(const LAS f16x8*)(lds + PG8_SA(b, h) + aoff + m * 2048 + k * 1024); } while (0)
; #define PG8_LDB(dst, b, h) do { _Pragma("unroll") for (int n = 0; n < 2; ++n) _Pragma("unroll") for (int k = 0; k < 2; ++k) dst[n][k] = *(const LAS f16x8*)(lds + PG8_SB(b, h) + boff + n * 2048 + k * 1024); } while (0)
; #define PG8_WAIT_V(n) asm volatile("s_waitcnt vmcnt(" #n ")" ::: "memory")
; #define PG8_WAIT_L(n) asm volatile("s_waitcnt lgkmcnt(" #n ")" ::: "memory")
; template <class Epi>
; __device__ __forceinline__ void gemm_phase(LAS unsigned char* lds, const Gemm g0, const StaticOrder& S, const Epi& E) {
;     ...
;         for (int t = 0; t < nt; t += 2) {
;             const bool last = (t == nt - 2);
;             if (Epi::PREF && last) E.prefetch(cur, wr, wc, lane);
;             const char* a1 = cA + (size_t)(t + 1) * kstep;
;             const char* a2 = last ? nA : cA + (size_t)(t + 2) * kstep; const char* b2 = last ? nB : cB + (size_t)(t + 2) * kstep;
;             const char* a3 = a2 + kstep; const char* b3 = b2 + kstep;
;             PG8_LDB(B0, 0, 0); PG8_SCHED; PG8_LDA(At, 0, 0); PG8_STAGE(PG8_SA(1, 1), a1 + hstep, voffA);
;             PG8_WAIT_L(8); PG8_BAR; PG8_WAIT_L(0); PG8_MMA(0, 0, At, B0); PG8_BAR; PG8_SCHED;
;             PG8_LDB(B1, 0, 1); PG8_STAGE(PG8_SB(0, 0), b2, voffB);
;             PG8_BAR; PG8_WAIT_L(0); PG8_MMA(0, 1, At, B1); PG8_BAR;
;             PG8_LDA(At, 0, 1); PG8_STAGE(PG8_SA(0, 0), a2, voffA);
;             PG8_BAR; PG8_WAIT_L(0); PG8_MMA(1, 0, At, B0); PG8_BAR; PG8_SCHED;
;             PG8_STAGE(PG8_SB(0, 1), b2 + hstep, voffB);
;             PG8_WAIT_V(6); PG8_BAR; PG8_MMA(1, 1, At, B1); PG8_BAR;
.LBB0_302:
	s_add_u32 s22, s6, 0xfff80080
	s_addc_u32 s23, s7, -1
	s_add_i32 s59, 0, 0x10000
	ds_read_b128 v[142:145], v161
	ds_read_b128 v[152:155], v161 offset:1024
	ds_read_b128 v[156:159], v161 offset:2048
	ds_read_b128 v[174:177], v161 offset:3072
	s_cmp_eq_u32 s58, 28
	s_cselect_b32 s37, s15, s23
	s_cselect_b32 s36, s52, s22
	s_cselect_b32 s35, s13, s53
	s_cselect_b32 s34, s24, s25
	s_add_i32 m0, s28, 0xc000
	ds_read_b128 v[178:181], v150
	ds_read_b128 v[182:185], v150 offset:1024
	ds_read_b128 v[186:189], v150 offset:2048
	ds_read_b128 v[190:193], v150 offset:3072
	ds_read_b128 v[194:197], v150 offset:4096
	ds_read_b128 v[198:201], v150 offset:5120
	ds_read_b128 v[202:205], v150 offset:6144
	ds_read_b128 v[206:209], v150 offset:7168
	global_load_lds_dwordx4 v140, s[6:7]
	s_add_i32 m0, s28, 0xe000
	s_nop 0
	global_load_lds_dwordx4 v138, s[6:7]
	s_waitcnt lgkmcnt(8)
	s_barrier
	s_waitcnt lgkmcnt(0)
	v_mfma_f32_16x16x32_f16 v[126:129], v[142:145], v[178:181], v[126:129]
	v_mfma_f32_16x16x32_f16 v[122:125], v[156:159], v[178:181], v[122:125]
	v_mfma_f32_16x16x32_f16 v[110:113], v[142:145], v[186:189], v[110:113]
	v_mfma_f32_16x16x32_f16 v[106:109], v[156:159], v[186:189], v[106:109]
	v_mfma_f32_16x16x32_f16 v[94:97], v[142:145], v[194:197], v[94:97]
	v_mfma_f32_16x16x32_f16 v[90:93], v[156:159], v[194:197], v[90:93]
	v_mfma_f32_16x16x32_f16 v[78:81], v[142:145], v[202:205], v[78:81]
	v_mfma_f32_16x16x32_f16 v[74:77], v[156:159], v[202:205], v[74:77]
	v_mfma_f32_16x16x32_f16 v[126:129], v[152:155], v[182:185], v[126:129]
	v_mfma_f32_16x16x32_f16 v[122:125], v[174:177], v[182:185], v[122:125]
	v_mfma_f32_16x16x32_f16 v[110:113], v[152:155], v[190:193], v[110:113]
	v_mfma_f32_16x16x32_f16 v[106:109], v[174:177], v[190:193], v[106:109]
	v_mfma_f32_16x16x32_f16 v[94:97], v[152:155], v[198:201], v[94:97]
	v_mfma_f32_16x16x32_f16 v[90:93], v[174:177], v[198:201], v[90:93]
	v_mfma_f32_16x16x32_f16 v[78:81], v[152:155], v[206:209], v[78:81]
	v_mfma_f32_16x16x32_f16 v[74:77], v[174:177], v[206:209], v[74:77]
	s_barrier
	s_add_i32 s61, 0, 0x14000
	s_add_i32 s22, s59, s19
	ds_read_b128 v[210:213], v161 offset:16384
	ds_read_b128 v[234:237], v161 offset:17408
	ds_read_b128 v[238:241], v161 offset:18432
	s_mov_b32 m0, s22
	ds_read_b128 v[242:245], v161 offset:19456
	global_load_lds_dwordx4 v134, s[34:35]
	s_add_i32 m0, s22, 0x2000
	s_nop 0
	global_load_lds_dwordx4 v130, s[34:35]
	s_barrier
	s_waitcnt lgkmcnt(0)
	v_mfma_f32_16x16x32_f16 v[118:121], v[210:213], v[178:181], v[118:121]
	v_mfma_f32_16x16x32_f16 v[114:117], v[238:241], v[178:181], v[114:117]
	v_mfma_f32_16x16x32_f16 v[102:105], v[210:213], v[186:189], v[102:105]
	v_mfma_f32_16x16x32_f16 v[98:101], v[238:241], v[186:189], v[98:101]
	v_mfma_f32_16x16x32_f16 v[86:89], v[210:213], v[194:197], v[86:89]
	v_mfma_f32_16x16x32_f16 v[82:85], v[238:241], v[194:197], v[82:85]
	v_mfma_f32_16x16x32_f16 v[70:73], v[210:213], v[202:205], v[70:73]
	v_mfma_f32_16x16x32_f16 v[66:69], v[238:241], v[202:205], v[66:69]
	v_mfma_f32_16x16x32_f16 v[118:121], v[234:237], v[182:185], v[118:121]
	v_mfma_f32_16x16x32_f16 v[114:117], v[242:245], v[182:185], v[114:117]
	v_mfma_f32_16x16x32_f16 v[102:105], v[234:237], v[190:193], v[102:105]
	v_mfma_f32_16x16x32_f16 v[98:101], v[242:245], v[190:193], v[98:101]
	v_mfma_f32_16x16x32_f16 v[86:89], v[234:237], v[198:201], v[86:89]
	v_mfma_f32_16x16x32_f16 v[82:85], v[242:245], v[198:201], v[82:85]
	v_mfma_f32_16x16x32_f16 v[70:73], v[234:237], v[206:209], v[70:73]
	v_mfma_f32_16x16x32_f16 v[66:69], v[242:245], v[206:209], v[66:69]
	s_mov_b32 m0, s28
	s_barrier
	ds_read_b128 v[178:181], v150 offset:16384
	ds_read_b128 v[182:185], v150 offset:17408
	ds_read_b128 v[186:189], v150 offset:18432
	ds_read_b128 v[190:193], v150 offset:19456
	ds_read_b128 v[194:197], v150 offset:20480
	ds_read_b128 v[198:201], v150 offset:21504
	ds_read_b128 v[202:205], v150 offset:22528
	ds_read_b128 v[206:209], v150 offset:23552
	global_load_lds_dwordx4 v136, s[36:37]
	s_mov_b32 m0, s29
	s_nop 0
	global_load_lds_dwordx4 v132, s[36:37]
	s_barrier
	s_waitcnt lgkmcnt(0)
	v_mfma_f32_16x16x32_f16 v[62:65], v[142:145], v[178:181], v[62:65]
	v_mfma_f32_16x16x32_f16 v[58:61], v[156:159], v[178:181], v[58:61]
	v_mfma_f32_16x16x32_f16 v[46:49], v[142:145], v[186:189], v[46:49]
	v_mfma_f32_16x16x32_f16 v[42:45], v[156:159], v[186:189], v[42:45]
	v_mfma_f32_16x16x32_f16 v[30:33], v[142:145], v[194:197], v[30:33]
	v_mfma_f32_16x16x32_f16 v[26:29], v[156:159], v[194:197], v[26:29]
	v_mfma_f32_16x16x32_f16 v[14:17], v[142:145], v[202:205], v[14:17]
	v_mfma_f32_16x16x32_f16 v[10:13], v[156:159], v[202:205], v[10:13]
	v_mfma_f32_16x16x32_f16 v[62:65], v[152:155], v[182:185], v[62:65]
	v_mfma_f32_16x16x32_f16 v[58:61], v[174:177], v[182:185], v[58:61]
	v_mfma_f32_16x16x32_f16 v[46:49], v[152:155], v[190:193], v[46:49]
	v_mfma_f32_16x16x32_f16 v[42:45], v[174:177], v[190:193], v[42:45]
	v_mfma_f32_16x16x32_f16 v[30:33], v[152:155], v[198:201], v[30:33]
	v_mfma_f32_16x16x32_f16 v[26:29], v[174:177], v[198:201], v[26:29]
	v_mfma_f32_16x16x32_f16 v[14:17], v[152:155], v[206:209], v[14:17]
	v_mfma_f32_16x16x32_f16 v[10:13], v[174:177], v[206:209], v[10:13]
	s_barrier
	s_add_u32 s22, s34, 0x80000
	s_addc_u32 s23, s35, 0
	s_add_i32 s59, s61, s19
	s_mov_b32 m0, s59
	s_nop 0
	global_load_lds_dwordx4 v134, s[22:23]
	s_add_i32 m0, s59, 0x2000
	s_nop 0
	global_load_lds_dwordx4 v130, s[22:23]
	s_waitcnt vmcnt(6)
	s_barrier
; #define PG8_STAGE(bufoff, gbase, voff) do { _Pragma("unroll") for (int _i = 0; _i < 2; ++_i) \
;         __builtin_amdgcn_global_load_lds((const unsigned*)((const char*)(gbase) + (voff)[_i]), (LAS unsigned*)(lds + (bufoff) + ldsw + _i * 8192), 16, 0, 0); } while (0)
; #define PG8_LDA(dst, b, h) do { _Pragma("unroll") for (int m = 0; m < 4; ++m) _Pragma("unroll") for (int k = 0; k < 2; ++k) dst[m][k] = *(const LAS f16x8*)(lds + PG8_SA(b, h) + aoff + m * 2048 + k * 1024); } while (0)
; #define PG8_LDB(dst, b, h) do { _Pragma("unroll") for (int n = 0; n < 2; ++n) _Pragma("unroll") for (int k = 0; k < 2; ++k) dst[n][k] = *(const LAS f16x8*)(lds + PG8_SB(b, h) + boff + n * 2048 + k * 1024); } while (0)
; #define PG8_MMA(ai, bj, At, Bt) do { __builtin_amdgcn_s_setprio(1); _Pragma("unroll") for (int m = 0; m < 4; ++m) _Pragma("unroll") for (int n = 0; n < 2; ++n) _Pragma("unroll") for (int k = 0; k < 2; ++k) \
;         acc[ai][bj][m][n] = __builtin_amdgcn_mfma_f32_16x16x32_f16(Bt[n][k], At[m][k], acc[ai][bj][m][n], 0, 0, 0); __builtin_amdgcn_s_setprio(0); } while (0)
; #define PG8_WAIT_V(n) asm volatile("s_waitcnt vmcnt(" #n ")" ::: "memory")
; #define PG8_WAIT_L(n) asm volatile("s_waitcnt lgkmcnt(" #n ")" ::: "memory")
; #define PG8_BAR __builtin_amdgcn_s_barrier()
; #define PG8_SCHED __builtin_amdgcn_sched_barrier(0)
; template <class Epi>
; __device__ __forceinline__ void gemm_phase(LAS unsigned char* lds, const Gemm g0, const StaticOrder& S, const Epi& E) {
;     ...
;             PG8_WAIT_V(6); PG8_BAR; PG8_MMA(1, 1, At, B1); PG8_BAR;
;             PG8_LDB(B0, 1, 0); PG8_SCHED; PG8_LDA(At, 1, 0); PG8_STAGE(PG8_SA(0, 1), a2 + hstep, voffA);
;             PG8_WAIT_L(8); PG8_BAR; PG8_WAIT_L(0); PG8_MMA(0, 0, At, B0); PG8_BAR; PG8_SCHED;
;             PG8_LDB(B1, 1, 1); PG8_STAGE(PG8_SB(1, 0), b3, voffB);
;             PG8_BAR; PG8_WAIT_L(0); PG8_MMA(0, 1, At, B1); PG8_BAR;
;             PG8_LDA(At, 1, 1); PG8_STAGE(PG8_SA(1, 0), a3, voffA);
	v_mfma_f32_16x16x32_f16 v[54:57], v[210:213], v[178:181], v[54:57]
	v_mfma_f32_16x16x32_f16 v[50:53], v[238:241], v[178:181], v[50:53]
	v_mfma_f32_16x16x32_f16 v[38:41], v[210:213], v[186:189], v[38:41]
	v_mfma_f32_16x16x32_f16 v[34:37], v[238:241], v[186:189], v[34:37]
	v_mfma_f32_16x16x32_f16 v[22:25], v[210:213], v[194:197], v[22:25]
	v_mfma_f32_16x16x32_f16 v[18:21], v[238:241], v[194:197], v[18:21]
	v_mfma_f32_16x16x32_f16 v[6:9], v[210:213], v[202:205], v[6:9]
	v_mfma_f32_16x16x32_f16 v[2:5], v[238:241], v[202:205], v[2:5]
	v_mfma_f32_16x16x32_f16 v[54:57], v[234:237], v[182:185], v[54:57]
	v_mfma_f32_16x16x32_f16 v[50:53], v[242:245], v[182:185], v[50:53]
	v_mfma_f32_16x16x32_f16 v[38:41], v[234:237], v[190:193], v[38:41]
	v_mfma_f32_16x16x32_f16 v[34:37], v[242:245], v[190:193], v[34:37]
	v_mfma_f32_16x16x32_f16 v[22:25], v[234:237], v[198:201], v[22:25]
	v_mfma_f32_16x16x32_f16 v[18:21], v[242:245], v[198:201], v[18:21]
	v_mfma_f32_16x16x32_f16 v[6:9], v[234:237], v[206:209], v[6:9]
	v_mfma_f32_16x16x32_f16 v[2:5], v[242:245], v[206:209], v[2:5]
	s_add_i32 s59, 0, 0x18000
	s_barrier
	ds_read_b128 v[142:145], v161 offset:32768
	ds_read_b128 v[152:155], v161 offset:33792
	ds_read_b128 v[156:159], v161 offset:34816
	ds_read_b128 v[174:177], v161 offset:35840
	s_add_u32 s22, s36, 0x80000
	s_addc_u32 s23, s37, 0
	s_mov_b32 m0, s31
	ds_read_b128 v[178:181], v150 offset:32768
	ds_read_b128 v[182:185], v150 offset:33792
	ds_read_b128 v[186:189], v150 offset:34816
	ds_read_b128 v[190:193], v150 offset:35840
	ds_read_b128 v[194:197], v150 offset:36864
	ds_read_b128 v[198:201], v150 offset:37888
	ds_read_b128 v[202:205], v150 offset:38912
	ds_read_b128 v[206:209], v150 offset:39936
	global_load_lds_dwordx4 v136, s[22:23]
	s_mov_b32 m0, s38
	s_nop 0
	global_load_lds_dwordx4 v132, s[22:23]
	s_waitcnt lgkmcnt(8)
	s_barrier
	s_waitcnt lgkmcnt(0)
	v_mfma_f32_16x16x32_f16 v[126:129], v[142:145], v[178:181], v[126:129]
	v_mfma_f32_16x16x32_f16 v[122:125], v[156:159], v[178:181], v[122:125]
	v_mfma_f32_16x16x32_f16 v[110:113], v[142:145], v[186:189], v[110:113]
	v_mfma_f32_16x16x32_f16 v[106:109], v[156:159], v[186:189], v[106:109]
	v_mfma_f32_16x16x32_f16 v[94:97], v[142:145], v[194:197], v[94:97]
	v_mfma_f32_16x16x32_f16 v[90:93], v[156:159], v[194:197], v[90:93]
	v_mfma_f32_16x16x32_f16 v[78:81], v[142:145], v[202:205], v[78:81]
	v_mfma_f32_16x16x32_f16 v[74:77], v[156:159], v[202:205], v[74:77]
	v_mfma_f32_16x16x32_f16 v[126:129], v[152:155], v[182:185], v[126:129]
	v_mfma_f32_16x16x32_f16 v[122:125], v[174:177], v[182:185], v[122:125]
	v_mfma_f32_16x16x32_f16 v[110:113], v[152:155], v[190:193], v[110:113]
	v_mfma_f32_16x16x32_f16 v[106:109], v[174:177], v[190:193], v[106:109]
	v_mfma_f32_16x16x32_f16 v[94:97], v[152:155], v[198:201], v[94:97]
	v_mfma_f32_16x16x32_f16 v[90:93], v[174:177], v[198:201], v[90:93]
	v_mfma_f32_16x16x32_f16 v[78:81], v[152:155], v[206:209], v[78:81]
	v_mfma_f32_16x16x32_f16 v[74:77], v[174:177], v[206:209], v[74:77]
	s_barrier
	s_add_i32 s61, 0, 0x1c000
	s_add_i32 s22, s59, s19
	s_mov_b32 m0, s22
	ds_read_b128 v[210:213], v161 offset:49152
	ds_read_b128 v[234:237], v161 offset:50176
	ds_read_b128 v[238:241], v161 offset:51200
	ds_read_b128 v[242:245], v161 offset:52224
	global_load_lds_dwordx4 v146, s[34:35]
	s_add_i32 m0, s22, 0x2000
	s_nop 0
	global_load_lds_dwordx4 v160, s[34:35]
	s_barrier
	s_waitcnt lgkmcnt(0)
	v_mfma_f32_16x16x32_f16 v[118:121], v[210:213], v[178:181], v[118:121]
	v_mfma_f32_16x16x32_f16 v[114:117], v[238:241], v[178:181], v[114:117]
	v_mfma_f32_16x16x32_f16 v[102:105], v[210:213], v[186:189], v[102:105]
	v_mfma_f32_16x16x32_f16 v[98:101], v[238:241], v[186:189], v[98:101]
	v_mfma_f32_16x16x32_f16 v[86:89], v[210:213], v[194:197], v[86:89]
	v_mfma_f32_16x16x32_f16 v[82:85], v[238:241], v[194:197], v[82:85]
	v_mfma_f32_16x16x32_f16 v[70:73], v[210:213], v[202:205], v[70:73]
	v_mfma_f32_16x16x32_f16 v[66:69], v[238:241], v[202:205], v[66:69]
	v_mfma_f32_16x16x32_f16 v[118:121], v[234:237], v[182:185], v[118:121]
	v_mfma_f32_16x16x32_f16 v[114:117], v[242:245], v[182:185], v[114:117]
	v_mfma_f32_16x16x32_f16 v[102:105], v[234:237], v[190:193], v[102:105]
	v_mfma_f32_16x16x32_f16 v[98:101], v[242:245], v[190:193], v[98:101]
	v_mfma_f32_16x16x32_f16 v[86:89], v[234:237], v[198:201], v[86:89]
	v_mfma_f32_16x16x32_f16 v[82:85], v[242:245], v[198:201], v[82:85]
	v_mfma_f32_16x16x32_f16 v[70:73], v[234:237], v[206:209], v[70:73]
	v_mfma_f32_16x16x32_f16 v[66:69], v[242:245], v[206:209], v[66:69]
	s_mov_b32 m0, s39
	s_barrier
	ds_read_b128 v[178:181], v150 offset:49152
	ds_read_b128 v[182:185], v150 offset:50176
	ds_read_b128 v[186:189], v150 offset:51200
	ds_read_b128 v[190:193], v150 offset:52224
	ds_read_b128 v[194:197], v150 offset:53248
	ds_read_b128 v[198:201], v150 offset:54272
	ds_read_b128 v[202:205], v150 offset:55296
	ds_read_b128 v[206:209], v150 offset:56320
	global_load_lds_dwordx4 v162, s[36:37]
	s_mov_b32 m0, s48
	s_nop 0
	global_load_lds_dwordx4 v164, s[36:37]
	s_barrier
; __device__ __forceinline__ float gelu_tanh(float x) { const float y = 1.5957691216057308f * (x + 0.044715f * x * x * x); return x * fast_rcp(1.0f + __expf(-y)); }
; #define PG8_STAGE(bufoff, gbase, voff) do { _Pragma("unroll") for (int _i = 0; _i < 2; ++_i) \
;         __builtin_amdgcn_global_load_lds((const unsigned*)((const char*)(gbase) + (voff)[_i]), (LAS unsigned*)(lds + (bufoff) + ldsw + _i * 8192), 16, 0, 0); } while (0)
; #define PG8_LDA(dst, b, h) do { _Pragma("unroll") for (int m = 0; m < 4; ++m) _Pragma("unroll") for (int k = 0; k < 2; ++k) dst[m][k] = *(const LAS f16x8*)(lds + PG8_SA(b, h) + aoff + m * 2048 + k * 1024); } while (0)
; #define PG8_MMA(ai, bj, At, Bt) do { __builtin_amdgcn_s_setprio(1); _Pragma("unroll") for (int m = 0; m < 4; ++m) _Pragma("unroll") for (int n = 0; n < 2; ++n) _Pragma("unroll") for (int k = 0; k < 2; ++k) \
;         acc[ai][bj][m][n] = __builtin_amdgcn_mfma_f32_16x16x32_f16(Bt[n][k], At[m][k], acc[ai][bj][m][n], 0, 0, 0); __builtin_amdgcn_s_setprio(0); } while (0)
; #define PG8_WAIT_V(n) asm volatile("s_waitcnt vmcnt(" #n ")" ::: "memory")
;     __device__ __forceinline__ void operator()(f32x4 (&acc)[2][2][4][2], const Unit& u, int wr, int wc, int fr, int fq) const {
;         const bool isy = u.pn < 8; h16* dst = isy ? ybr : xpre; const int colb = (isy ? u.pn : u.pn - 8) * BM + wc * 32 + 8 * fq;
;         const int row0 = u.pm * BM + wr * 64 + fr;
; #pragma unroll
;         for (int ai = 0; ai < 2; ++ai)
; #pragma unroll
;             for (int m = 0; m < 4; ++m) { h16* rowp = dst + (size_t)(row0 + ai * HALF + m * 16) * DM + colb;
; #pragma unroll
;                 for (int bj = 0; bj < 2; ++bj) { f32x4 v0 = acc[ai][bj][m][0], v1 = acc[ai][bj][m][1];
;                     if (isy) {
; #pragma unroll
;                         for (int j = 0; j < 4; ++j) { v0[j] = gelu_tanh(v0[j]); v1[j] = gelu_tanh(v1[j]); } }
; template <class Epi>
; __device__ __forceinline__ void gemm_phase(LAS unsigned char* lds, const Gemm g0, const StaticOrder& S, const Epi& E) {
;     ...
;             PG8_BAR; PG8_WAIT_L(0); PG8_MMA(0, 1, At, B1); PG8_BAR;
;             PG8_LDA(At, 1, 1); PG8_STAGE(PG8_SA(1, 0), a3, voffA);
;             PG8_BAR; PG8_WAIT_L(0); PG8_MMA(1, 0, At, B0); PG8_BAR; PG8_SCHED;
;             PG8_STAGE(PG8_SB(1, 1), b3 + hstep, voffB);
;             PG8_WAIT_V(6); PG8_BAR; PG8_MMA(1, 1, At, B1); PG8_BAR;
;         }
	s_waitcnt lgkmcnt(0)
	v_mfma_f32_16x16x32_f16 v[62:65], v[142:145], v[178:181], v[62:65]
	v_mfma_f32_16x16x32_f16 v[58:61], v[156:159], v[178:181], v[58:61]
	v_mfma_f32_16x16x32_f16 v[46:49], v[142:145], v[186:189], v[46:49]
	v_mfma_f32_16x16x32_f16 v[42:45], v[156:159], v[186:189], v[42:45]
	v_mfma_f32_16x16x32_f16 v[30:33], v[142:145], v[194:197], v[30:33]
	v_mfma_f32_16x16x32_f16 v[26:29], v[156:159], v[194:197], v[26:29]
	v_mfma_f32_16x16x32_f16 v[14:17], v[142:145], v[202:205], v[14:17]
	v_mfma_f32_16x16x32_f16 v[10:13], v[156:159], v[202:205], v[10:13]
	v_mfma_f32_16x16x32_f16 v[62:65], v[152:155], v[182:185], v[62:65]
	v_mfma_f32_16x16x32_f16 v[58:61], v[174:177], v[182:185], v[58:61]
	v_mfma_f32_16x16x32_f16 v[46:49], v[152:155], v[190:193], v[46:49]
	v_mfma_f32_16x16x32_f16 v[42:45], v[174:177], v[190:193], v[42:45]
	v_mfma_f32_16x16x32_f16 v[30:33], v[152:155], v[198:201], v[30:33]
	v_mfma_f32_16x16x32_f16 v[26:29], v[174:177], v[198:201], v[26:29]
	v_mfma_f32_16x16x32_f16 v[14:17], v[152:155], v[206:209], v[14:17]
	v_mfma_f32_16x16x32_f16 v[10:13], v[174:177], v[206:209], v[10:13]
	s_barrier
	s_add_u32 s22, s34, 0x80080
	s_addc_u32 s23, s35, 0
	s_add_i32 s34, s61, s19
	s_mov_b32 m0, s34
	s_nop 0
	global_load_lds_dwordx4 v134, s[22:23]
	s_add_i32 m0, s34, 0x2000
	s_nop 0
	global_load_lds_dwordx4 v130, s[22:23]
	s_waitcnt vmcnt(6)
	s_barrier
	v_mfma_f32_16x16x32_f16 v[54:57], v[210:213], v[178:181], v[54:57]
	v_mfma_f32_16x16x32_f16 v[50:53], v[238:241], v[178:181], v[50:53]
	v_mfma_f32_16x16x32_f16 v[38:41], v[210:213], v[186:189], v[38:41]
	v_mfma_f32_16x16x32_f16 v[34:37], v[238:241], v[186:189], v[34:37]
	v_mfma_f32_16x16x32_f16 v[22:25], v[210:213], v[194:197], v[22:25]
	v_mfma_f32_16x16x32_f16 v[18:21], v[238:241], v[194:197], v[18:21]
	v_mfma_f32_16x16x32_f16 v[6:9], v[210:213], v[202:205], v[6:9]
	v_mfma_f32_16x16x32_f16 v[2:5], v[238:241], v[202:205], v[2:5]
	v_mfma_f32_16x16x32_f16 v[54:57], v[234:237], v[182:185], v[54:57]
	v_mfma_f32_16x16x32_f16 v[50:53], v[242:245], v[182:185], v[50:53]
	v_mfma_f32_16x16x32_f16 v[38:41], v[234:237], v[190:193], v[38:41]
	v_mfma_f32_16x16x32_f16 v[34:37], v[242:245], v[190:193], v[34:37]
	v_mfma_f32_16x16x32_f16 v[22:25], v[234:237], v[198:201], v[22:25]
	v_mfma_f32_16x16x32_f16 v[18:21], v[242:245], v[198:201], v[18:21]
	v_mfma_f32_16x16x32_f16 v[6:9], v[234:237], v[206:209], v[6:9]
	v_mfma_f32_16x16x32_f16 v[2:5], v[242:245], v[206:209], v[2:5]
	s_add_i32 s58, s58, 2
	s_add_u32 s25, s25, 0x100
	s_addc_u32 s53, s53, 0
	s_add_u32 s6, s6, 0x100
	s_addc_u32 s7, s7, 0
	s_cmp_gt_u32 s58, 29
	s_barrier
	s_cbranch_scc0 .LBB0_302
	s_cmp_lt_i32 s51, 8
	s_cselect_b64 s[34:35], -1, 0
	s_cmp_gt_i32 s51, 7
	s_cbranch_scc1 .LBB0_305
	v_mul_f32_e32 v143, 0x3d372713, v122
	v_mul_f32_e32 v143, v122, v143
	v_fma_f32 v143, v122, v143, v122
	v_mul_f32_e32 v143, 0xbfcc422a, v143
	v_mul_f32_e32 v143, 0x3fb8aa3b, v143
	v_exp_f32_e32 v143, v143
	v_mul_f32_e32 v142, 0x3d372713, v126
	v_mul_f32_e32 v142, v126, v142
	v_fma_f32 v142, v126, v142, v126
	v_add_f32_e32 v143, 1.0, v143
	v_rcp_f32_e32 v144, v143
	v_mul_f32_e32 v143, 0x3d372713, v127
	v_mul_f32_e32 v143, v127, v143
	v_fma_f32 v143, v127, v143, v127
	v_mul_f32_e32 v142, 0xbfcc422a, v142
	v_mul_f32_e32 v143, 0xbfcc422a, v143
	v_mul_f32_e32 v142, 0x3fb8aa3b, v142
	v_mul_f32_e32 v143, 0x3fb8aa3b, v143
	v_mul_f32_e32 v147, 0x3d372713, v124
	v_exp_f32_e32 v142, v142
	v_exp_f32_e32 v143, v143
	v_mul_f32_e32 v147, v124, v147
	v_fma_f32 v147, v124, v147, v124
	v_mul_f32_e32 v147, 0xbfcc422a, v147
	v_mul_f32_e32 v147, 0x3fb8aa3b, v147
	v_add_f32_e32 v142, 1.0, v142
	v_add_f32_e32 v143, 1.0, v143
	v_exp_f32_e32 v147, v147
	v_rcp_f32_e32 v142, v142
	v_rcp_f32_e32 v143, v143
	v_mul_f32_e32 v145, 0x3d372713, v123
	v_add_f32_e32 v147, 1.0, v147
	v_mul_f32_e32 v146, 0x3d372713, v128
	v_rcp_f32_e32 v152, v147
	v_mul_f32_e32 v147, 0x3d372713, v129
	v_pk_mul_f32 v[126:127], v[126:127], v[142:143]
	v_mul_f32_e32 v142, 0x3d372713, v125
	v_mul_f32_e32 v145, v123, v145
	v_mul_f32_e32 v146, v128, v146
	v_mul_f32_e32 v147, v129, v147
	v_mul_f32_e32 v142, v125, v142
	v_fma_f32 v145, v123, v145, v123
	v_fma_f32 v146, v128, v146, v128
	v_fma_f32 v147, v129, v147, v129
	v_fma_f32 v142, v125, v142, v125
	v_mul_f32_e32 v145, 0xbfcc422a, v145
	v_mul_f32_e32 v146, 0xbfcc422a, v146
	v_mul_f32_e32 v147, 0xbfcc422a, v147
	v_mul_f32_e32 v142, 0xbfcc422a, v142
	v_mul_f32_e32 v145, 0x3fb8aa3b, v145
	v_mul_f32_e32 v146, 0x3fb8aa3b, v146
	v_mul_f32_e32 v147, 0x3fb8aa3b, v147
	v_mul_f32_e32 v142, 0x3fb8aa3b, v142
	v_exp_f32_e32 v145, v145
	v_exp_f32_e32 v146, v146
	v_exp_f32_e32 v147, v147
	v_exp_f32_e32 v142, v142
	v_add_f32_e32 v145, 1.0, v145
	v_add_f32_e32 v146, 1.0, v146
	v_add_f32_e32 v147, 1.0, v147
	v_add_f32_e32 v142, 1.0, v142
	v_rcp_f32_e32 v145, v145
	v_rcp_f32_e32 v146, v146
	v_rcp_f32_e32 v147, v147
	v_rcp_f32_e32 v153, v142
	v_pk_mul_f32 v[122:123], v[122:123], v[144:145]
	v_pk_mul_f32 v[128:129], v[128:129], v[146:147]
	v_pk_mul_f32 v[124:125], v[124:125], v[152:153]

;     __device__ __forceinline__ void prefetch(const Unit& u, int wr, int wc, int lane) const { lnfold_prefetch(vl, stats, gW, bW, u, wr, wc, lane); }
;     __device__ __forceinline__ void prefetch(const Unit& u, int wr, int wc, int lane) const { lnfold_prefetch(vl, stats, gW, bW, u, wr, wc, lane); }
; #define PG8_STAGE(bufoff, gbase, voff) do { _Pragma("unroll") for (int _i = 0; _i < 2; ++_i) \
;         __builtin_amdgcn_global_load_lds((const unsigned*)((const char*)(gbase) + (voff)[_i]), (LAS unsigned*)(lds + (bufoff) + ldsw + _i * 8192), 16, 0, 0); } while (0)
; #define PG8_LDA(dst, b, h) do { _Pragma("unroll") for (int m = 0; m < 4; ++m) _Pragma("unroll") for (int k = 0; k < 2; ++k) dst[m][k] = *(const LAS f16x8*)(lds + PG8_SA(b, h) + aoff + m * 2048 + k * 1024); } while (0)
; #define PG8_LDB(dst, b, h) do { _Pragma("unroll") for (int n = 0; n < 2; ++n) _Pragma("unroll") for (int k = 0; k < 2; ++k) dst[n][k] = *(const LAS f16x8*)(lds + PG8_SB(b, h) + boff + n * 2048 + k * 1024); } while (0)
; #define PG8_WAIT_V(n) asm volatile("s_waitcnt vmcnt(" #n ")" ::: "memory")
; #define PG8_WAIT_L(n) asm volatile("s_waitcnt lgkmcnt(" #n ")" ::: "memory")
; template <class Epi>
; __device__ __forceinline__ void gemm_phase(LAS unsigned char* lds, const Gemm g0, const StaticOrder& S, const Epi& E) {
;     ...
;         for (int t = 0; t < nt; t += 2) {
;             const bool last = (t == nt - 2);
;             if (Epi::PREF && last) E.prefetch(cur, wr, wc, lane);
;             const char* a1 = cA + (size_t)(t + 1) * kstep;
;             const char* a2 = last ? nA : cA + (size_t)(t + 2) * kstep; const char* b2 = last ? nB : cB + (size_t)(t + 2) * kstep;
;             const char* a3 = a2 + kstep; const char* b3 = b2 + kstep;
;             PG8_LDB(B0, 0, 0); PG8_SCHED; PG8_LDA(At, 0, 0); PG8_STAGE(PG8_SA(1, 1), a1 + hstep, voffA);
;             PG8_WAIT_L(8); PG8_BAR; PG8_WAIT_L(0); PG8_MMA(0, 0, At, B0); PG8_BAR; PG8_SCHED;
;             PG8_LDB(B1, 0, 1); PG8_STAGE(PG8_SB(0, 0), b2, voffB);
;             PG8_BAR; PG8_WAIT_L(0); PG8_MMA(0, 1, At, B1); PG8_BAR;
;             PG8_LDA(At, 0, 1); PG8_STAGE(PG8_SA(0, 0), a2, voffA);
;             PG8_BAR; PG8_WAIT_L(0); PG8_MMA(1, 0, At, B0); PG8_BAR; PG8_SCHED;
;             PG8_STAGE(PG8_SB(0, 1), b2 + hstep, voffB);
;             PG8_WAIT_V(6); PG8_BAR; PG8_MMA(1, 1, At, B1); PG8_BAR;
.LBB0_512:
	s_add_u32 s23, s12, 0xfff80080
	s_addc_u32 s48, s13, -1
	s_add_i32 s90, 0, 0x10000
	ds_read_b128 v[122:125], v165
	ds_read_b128 v[126:129], v165 offset:1024
	ds_read_b128 v[138:141], v165 offset:2048
	ds_read_b128 v[142:145], v165 offset:3072
	s_cmp_eq_u32 s22, 28
	s_cselect_b32 s51, s15, s48
	s_cselect_b32 s50, s24, s23
	s_cselect_b32 s49, s25, vcc_hi
	s_cselect_b32 s48, s53, vcc_lo
	s_add_i32 m0, s71, 0xc000
	ds_read_b128 v[146:149], v210
	ds_read_b128 v[150:153], v210 offset:1024
	ds_read_b128 v[154:157], v210 offset:2048
	ds_read_b128 v[158:161], v210 offset:3072
	ds_read_b128 v[188:191], v210 offset:4096
	ds_read_b128 v[192:195], v210 offset:5120
	ds_read_b128 v[196:199], v210 offset:6144
	ds_read_b128 v[200:203], v210 offset:7168
	global_load_lds_dwordx4 v186, s[12:13]
	s_add_i32 m0, s71, 0xe000
	s_nop 0
	global_load_lds_dwordx4 v184, s[12:13]
	s_waitcnt lgkmcnt(8)
	s_barrier
	s_waitcnt lgkmcnt(0)
	v_mfma_f32_16x16x32_f16 v[134:137], v[122:125], v[146:149], v[134:137]
	v_mfma_f32_16x16x32_f16 v[130:133], v[138:141], v[146:149], v[130:133]
	v_mfma_f32_16x16x32_f16 v[110:113], v[122:125], v[154:157], v[110:113]
	v_mfma_f32_16x16x32_f16 v[106:109], v[138:141], v[154:157], v[106:109]
	v_mfma_f32_16x16x32_f16 v[94:97], v[122:125], v[188:191], v[94:97]
	v_mfma_f32_16x16x32_f16 v[90:93], v[138:141], v[188:191], v[90:93]
	v_mfma_f32_16x16x32_f16 v[78:81], v[122:125], v[196:199], v[78:81]
	v_mfma_f32_16x16x32_f16 v[74:77], v[138:141], v[196:199], v[74:77]
	v_mfma_f32_16x16x32_f16 v[134:137], v[126:129], v[150:153], v[134:137]
	v_mfma_f32_16x16x32_f16 v[130:133], v[142:145], v[150:153], v[130:133]
	v_mfma_f32_16x16x32_f16 v[110:113], v[126:129], v[158:161], v[110:113]
	v_mfma_f32_16x16x32_f16 v[106:109], v[142:145], v[158:161], v[106:109]
	v_mfma_f32_16x16x32_f16 v[94:97], v[126:129], v[192:195], v[94:97]
	v_mfma_f32_16x16x32_f16 v[90:93], v[142:145], v[192:195], v[90:93]
	v_mfma_f32_16x16x32_f16 v[78:81], v[126:129], v[200:203], v[78:81]
	v_mfma_f32_16x16x32_f16 v[74:77], v[142:145], v[200:203], v[74:77]
	s_barrier
	s_add_i32 s23, 0, 0x14000
	s_add_i32 s90, s90, s75
	ds_read_b128 v[212:215], v165 offset:16384
	ds_read_b128 v[234:237], v165 offset:17408
	ds_read_b128 v[238:241], v165 offset:18432
	ds_read_b128 v[242:245], v165 offset:19456
	v_add_u32_e32 v162, 0x80, v178
	s_mov_b32 m0, s90
	s_nop 0
	global_load_lds_dwordx4 v178, s[48:49]
	s_add_i32 m0, s90, 0x2000
	s_nop 0
	global_load_lds_dwordx4 v174, s[48:49]
	s_barrier
	s_waitcnt lgkmcnt(0)
	v_mfma_f32_16x16x32_f16 v[118:121], v[212:215], v[146:149], v[118:121]
	v_mfma_f32_16x16x32_f16 v[114:117], v[238:241], v[146:149], v[114:117]
	v_mfma_f32_16x16x32_f16 v[102:105], v[212:215], v[154:157], v[102:105]
	v_mfma_f32_16x16x32_f16 v[98:101], v[238:241], v[154:157], v[98:101]
	v_mfma_f32_16x16x32_f16 v[86:89], v[212:215], v[188:191], v[86:89]
	v_mfma_f32_16x16x32_f16 v[82:85], v[238:241], v[188:191], v[82:85]
	v_mfma_f32_16x16x32_f16 v[70:73], v[212:215], v[196:199], v[70:73]
	v_mfma_f32_16x16x32_f16 v[66:69], v[238:241], v[196:199], v[66:69]
	v_mfma_f32_16x16x32_f16 v[118:121], v[234:237], v[150:153], v[118:121]
	v_mfma_f32_16x16x32_f16 v[114:117], v[242:245], v[150:153], v[114:117]
	v_mfma_f32_16x16x32_f16 v[102:105], v[234:237], v[158:161], v[102:105]
	v_mfma_f32_16x16x32_f16 v[98:101], v[242:245], v[158:161], v[98:101]
	v_mfma_f32_16x16x32_f16 v[86:89], v[234:237], v[192:195], v[86:89]
	v_mfma_f32_16x16x32_f16 v[82:85], v[242:245], v[192:195], v[82:85]
	v_mfma_f32_16x16x32_f16 v[70:73], v[234:237], v[200:203], v[70:73]
	v_mfma_f32_16x16x32_f16 v[66:69], v[242:245], v[200:203], v[66:69]
	s_mov_b32 m0, s71
	v_lshl_add_u64 v[170:171], s[50:51], 0, v[180:181]
	s_barrier
	ds_read_b128 v[146:149], v210 offset:16384
	ds_read_b128 v[150:153], v210 offset:17408
	ds_read_b128 v[154:157], v210 offset:18432
	ds_read_b128 v[158:161], v210 offset:19456
	ds_read_b128 v[188:191], v210 offset:20480
	ds_read_b128 v[192:195], v210 offset:21504
	ds_read_b128 v[196:199], v210 offset:22528
	ds_read_b128 v[200:203], v210 offset:23552
	global_load_lds_dwordx4 v[170:171], off
	v_lshl_add_u64 v[172:173], s[50:51], 0, v[176:177]
	s_mov_b32 m0, s61
	s_nop 0
	global_load_lds_dwordx4 v[172:173], off
	s_barrier
	s_waitcnt lgkmcnt(0)
	v_mfma_f32_16x16x32_f16 v[62:65], v[122:125], v[146:149], v[62:65]
	v_mfma_f32_16x16x32_f16 v[58:61], v[138:141], v[146:149], v[58:61]
	v_mfma_f32_16x16x32_f16 v[46:49], v[122:125], v[154:157], v[46:49]
	v_mfma_f32_16x16x32_f16 v[42:45], v[138:141], v[154:157], v[42:45]
	v_mfma_f32_16x16x32_f16 v[30:33], v[122:125], v[188:191], v[30:33]
	v_mfma_f32_16x16x32_f16 v[26:29], v[138:141], v[188:191], v[26:29]
	v_mfma_f32_16x16x32_f16 v[14:17], v[122:125], v[196:199], v[14:17]
	v_mfma_f32_16x16x32_f16 v[10:13], v[138:141], v[196:199], v[10:13]
	v_mfma_f32_16x16x32_f16 v[62:65], v[126:129], v[150:153], v[62:65]
	v_mfma_f32_16x16x32_f16 v[58:61], v[142:145], v[150:153], v[58:61]
	v_mfma_f32_16x16x32_f16 v[46:49], v[126:129], v[158:161], v[46:49]
	v_mfma_f32_16x16x32_f16 v[42:45], v[142:145], v[158:161], v[42:45]
	v_mfma_f32_16x16x32_f16 v[30:33], v[126:129], v[192:195], v[30:33]
	v_mfma_f32_16x16x32_f16 v[26:29], v[142:145], v[192:195], v[26:29]
	v_mfma_f32_16x16x32_f16 v[14:17], v[126:129], v[200:203], v[14:17]
	v_mfma_f32_16x16x32_f16 v[10:13], v[142:145], v[200:203], v[10:13]
	s_barrier
	s_add_u32 s90, s48, 0x80000
	s_addc_u32 s91, s49, 0
	s_add_i32 s23, s23, s75
	s_mov_b32 m0, s23
	s_nop 0
	global_load_lds_dwordx4 v178, s[90:91]
	s_add_i32 m0, s23, 0x2000
	s_nop 0
	global_load_lds_dwordx4 v174, s[90:91]
	s_waitcnt vmcnt(6)
	s_barrier
; #define PG8_STAGE(bufoff, gbase, voff) do { _Pragma("unroll") for (int _i = 0; _i < 2; ++_i) \
;         __builtin_amdgcn_global_load_lds((const unsigned*)((const char*)(gbase) + (voff)[_i]), (LAS unsigned*)(lds + (bufoff) + ldsw + _i * 8192), 16, 0, 0); } while (0)
; #define PG8_LDA(dst, b, h) do { _Pragma("unroll") for (int m = 0; m < 4; ++m) _Pragma("unroll") for (int k = 0; k < 2; ++k) dst[m][k] = *(const LAS f16x8*)(lds + PG8_SA(b, h) + aoff + m * 2048 + k * 1024); } while (0)
; #define PG8_LDB(dst, b, h) do { _Pragma("unroll") for (int n = 0; n < 2; ++n) _Pragma("unroll") for (int k = 0; k < 2; ++k) dst[n][k] = *(const LAS f16x8*)(lds + PG8_SB(b, h) + boff + n * 2048 + k * 1024); } while (0)
; #define PG8_MMA(ai, bj, At, Bt) do { __builtin_amdgcn_s_setprio(1); _Pragma("unroll") for (int m = 0; m < 4; ++m) _Pragma("unroll") for (int n = 0; n < 2; ++n) _Pragma("unroll") for (int k = 0; k < 2; ++k) \
;         acc[ai][bj][m][n] = __builtin_amdgcn_mfma_f32_16x16x32_f16(Bt[n][k], At[m][k], acc[ai][bj][m][n], 0, 0, 0); __builtin_amdgcn_s_setprio(0); } while (0)
; #define PG8_WAIT_V(n) asm volatile("s_waitcnt vmcnt(" #n ")" ::: "memory")
; #define PG8_WAIT_L(n) asm volatile("s_waitcnt lgkmcnt(" #n ")" ::: "memory")
; #define PG8_BAR __builtin_amdgcn_s_barrier()
; #define PG8_SCHED __builtin_amdgcn_sched_barrier(0)
; template <class Epi>
; __device__ __forceinline__ void gemm_phase(LAS unsigned char* lds, const Gemm g0, const StaticOrder& S, const Epi& E) {
;     ...
;             PG8_WAIT_V(6); PG8_BAR; PG8_MMA(1, 1, At, B1); PG8_BAR;
;             PG8_LDB(B0, 1, 0); PG8_SCHED; PG8_LDA(At, 1, 0); PG8_STAGE(PG8_SA(0, 1), a2 + hstep, voffA);
;             PG8_WAIT_L(8); PG8_BAR; PG8_WAIT_L(0); PG8_MMA(0, 0, At, B0); PG8_BAR; PG8_SCHED;
;             PG8_LDB(B1, 1, 1); PG8_STAGE(PG8_SB(1, 0), b3, voffB);
;             PG8_BAR; PG8_WAIT_L(0); PG8_MMA(0, 1, At, B1); PG8_BAR;
;             PG8_LDA(At, 1, 1); PG8_STAGE(PG8_SA(1, 0), a3, voffA);
	v_mfma_f32_16x16x32_f16 v[54:57], v[212:215], v[146:149], v[54:57]
	v_mfma_f32_16x16x32_f16 v[50:53], v[238:241], v[146:149], v[50:53]
	v_mfma_f32_16x16x32_f16 v[38:41], v[212:215], v[154:157], v[38:41]
	v_mfma_f32_16x16x32_f16 v[34:37], v[238:241], v[154:157], v[34:37]
	v_mfma_f32_16x16x32_f16 v[22:25], v[212:215], v[188:191], v[22:25]
	v_mfma_f32_16x16x32_f16 v[18:21], v[238:241], v[188:191], v[18:21]
	v_mfma_f32_16x16x32_f16 v[6:9], v[212:215], v[196:199], v[6:9]
	v_mfma_f32_16x16x32_f16 v[2:5], v[238:241], v[196:199], v[2:5]
	v_mfma_f32_16x16x32_f16 v[54:57], v[234:237], v[150:153], v[54:57]
	v_mfma_f32_16x16x32_f16 v[50:53], v[242:245], v[150:153], v[50:53]
	v_mfma_f32_16x16x32_f16 v[38:41], v[234:237], v[158:161], v[38:41]
	v_mfma_f32_16x16x32_f16 v[34:37], v[242:245], v[158:161], v[34:37]
	v_mfma_f32_16x16x32_f16 v[22:25], v[234:237], v[192:195], v[22:25]
	v_mfma_f32_16x16x32_f16 v[18:21], v[242:245], v[192:195], v[18:21]
	v_mfma_f32_16x16x32_f16 v[6:9], v[234:237], v[200:203], v[6:9]
	v_mfma_f32_16x16x32_f16 v[2:5], v[242:245], v[200:203], v[2:5]
	s_add_i32 s23, 0, 0x18000
	s_barrier
	ds_read_b128 v[122:125], v165 offset:32768
	ds_read_b128 v[126:129], v165 offset:33792
	ds_read_b128 v[138:141], v165 offset:34816
	ds_read_b128 v[142:145], v165 offset:35840
	s_add_u32 s50, s50, 0x80000
	s_addc_u32 s51, s51, 0
	s_mov_b32 m0, s74
	ds_read_b128 v[146:149], v210 offset:32768
	ds_read_b128 v[150:153], v210 offset:33792
	ds_read_b128 v[154:157], v210 offset:34816
	ds_read_b128 v[158:161], v210 offset:35840
	ds_read_b128 v[188:191], v210 offset:36864
	ds_read_b128 v[192:195], v210 offset:37888
	ds_read_b128 v[196:199], v210 offset:38912
	ds_read_b128 v[200:203], v210 offset:39936
	global_load_lds_dwordx4 v180, s[50:51]
	s_mov_b32 m0, s18
	s_nop 0
	global_load_lds_dwordx4 v176, s[50:51]
	s_waitcnt lgkmcnt(8)
	s_barrier
	s_waitcnt lgkmcnt(0)
	v_mfma_f32_16x16x32_f16 v[134:137], v[122:125], v[146:149], v[134:137]
	v_mfma_f32_16x16x32_f16 v[130:133], v[138:141], v[146:149], v[130:133]
	v_mfma_f32_16x16x32_f16 v[110:113], v[122:125], v[154:157], v[110:113]
	v_mfma_f32_16x16x32_f16 v[106:109], v[138:141], v[154:157], v[106:109]
	v_mfma_f32_16x16x32_f16 v[94:97], v[122:125], v[188:191], v[94:97]
	v_mfma_f32_16x16x32_f16 v[90:93], v[138:141], v[188:191], v[90:93]
	v_mfma_f32_16x16x32_f16 v[78:81], v[122:125], v[196:199], v[78:81]
	v_mfma_f32_16x16x32_f16 v[74:77], v[138:141], v[196:199], v[74:77]
	v_mfma_f32_16x16x32_f16 v[134:137], v[126:129], v[150:153], v[134:137]
	v_mfma_f32_16x16x32_f16 v[130:133], v[142:145], v[150:153], v[130:133]
	v_mfma_f32_16x16x32_f16 v[110:113], v[126:129], v[158:161], v[110:113]
	v_mfma_f32_16x16x32_f16 v[106:109], v[142:145], v[158:161], v[106:109]
	v_mfma_f32_16x16x32_f16 v[94:97], v[126:129], v[192:195], v[94:97]
	v_mfma_f32_16x16x32_f16 v[90:93], v[142:145], v[192:195], v[90:93]
	v_mfma_f32_16x16x32_f16 v[78:81], v[126:129], v[200:203], v[78:81]
	v_mfma_f32_16x16x32_f16 v[74:77], v[142:145], v[200:203], v[74:77]
	s_barrier
	s_add_i32 s50, 0, 0x1c000
	s_add_i32 s23, s23, s75
	s_mov_b32 m0, s23
	ds_read_b128 v[212:215], v165 offset:49152
	ds_read_b128 v[234:237], v165 offset:50176
	ds_read_b128 v[238:241], v165 offset:51200
	ds_read_b128 v[242:245], v165 offset:52224
	global_load_lds_dwordx4 v162, s[48:49]
	s_add_i32 m0, s23, 0x2000
	s_nop 0
	global_load_lds_dwordx4 v164, s[48:49]
	s_barrier
	s_waitcnt lgkmcnt(0)
	v_mfma_f32_16x16x32_f16 v[118:121], v[212:215], v[146:149], v[118:121]
	v_mfma_f32_16x16x32_f16 v[114:117], v[238:241], v[146:149], v[114:117]
	v_mfma_f32_16x16x32_f16 v[102:105], v[212:215], v[154:157], v[102:105]
	v_mfma_f32_16x16x32_f16 v[98:101], v[238:241], v[154:157], v[98:101]
	v_mfma_f32_16x16x32_f16 v[86:89], v[212:215], v[188:191], v[86:89]
	v_mfma_f32_16x16x32_f16 v[82:85], v[238:241], v[188:191], v[82:85]
	v_mfma_f32_16x16x32_f16 v[70:73], v[212:215], v[196:199], v[70:73]
	v_mfma_f32_16x16x32_f16 v[66:69], v[238:241], v[196:199], v[66:69]
	v_mfma_f32_16x16x32_f16 v[118:121], v[234:237], v[150:153], v[118:121]
	v_mfma_f32_16x16x32_f16 v[114:117], v[242:245], v[150:153], v[114:117]
	v_mfma_f32_16x16x32_f16 v[102:105], v[234:237], v[158:161], v[102:105]
	v_mfma_f32_16x16x32_f16 v[98:101], v[242:245], v[158:161], v[98:101]
	v_mfma_f32_16x16x32_f16 v[86:89], v[234:237], v[192:195], v[86:89]
	v_mfma_f32_16x16x32_f16 v[82:85], v[242:245], v[192:195], v[82:85]
	v_mfma_f32_16x16x32_f16 v[70:73], v[234:237], v[200:203], v[70:73]
	v_mfma_f32_16x16x32_f16 v[66:69], v[242:245], v[200:203], v[66:69]
	s_mov_b32 m0, s28
	v_lshl_add_u64 v[162:163], v[170:171], 0, s[64:65]
	s_barrier
; #define GAS __attribute__((address_space(1)))
; #define PG8_STAGE(bufoff, gbase, voff) do { _Pragma("unroll") for (int _i = 0; _i < 2; ++_i) \
;         __builtin_amdgcn_global_load_lds((const unsigned*)((const char*)(gbase) + (voff)[_i]), (LAS unsigned*)(lds + (bufoff) + ldsw + _i * 8192), 16, 0, 0); } while (0)
; #define PG8_LDA(dst, b, h) do { _Pragma("unroll") for (int m = 0; m < 4; ++m) _Pragma("unroll") for (int k = 0; k < 2; ++k) dst[m][k] = *(const LAS f16x8*)(lds + PG8_SA(b, h) + aoff + m * 2048 + k * 1024); } while (0)
; #define PG8_MMA(ai, bj, At, Bt) do { __builtin_amdgcn_s_setprio(1); _Pragma("unroll") for (int m = 0; m < 4; ++m) _Pragma("unroll") for (int n = 0; n < 2; ++n) _Pragma("unroll") for (int k = 0; k < 2; ++k) \
;         acc[ai][bj][m][n] = __builtin_amdgcn_mfma_f32_16x16x32_f16(Bt[n][k], At[m][k], acc[ai][bj][m][n], 0, 0, 0); __builtin_amdgcn_s_setprio(0); } while (0)
; #define PG8_WAIT_V(n) asm volatile("s_waitcnt vmcnt(" #n ")" ::: "memory")
; #define PG8_WAIT_L(n) asm volatile("s_waitcnt lgkmcnt(" #n ")" ::: "memory")
; #define PG8_BAR __builtin_amdgcn_s_barrier()
; #define PG8_SCHED __builtin_amdgcn_sched_barrier(0)
;     __device__ __forceinline__ void operator()(f32x4 (&acc)[2][2][4][2], const Unit& u, int wr, int wc, int fr, int fq) const {
;     ...
;         { const int lane = fr + 16 * fq, cL = u.pn * BM + wc * 32 + (lane < 32 ? lane : 96 + lane);
;           float vg = 0.f, vb = 0.f, vt = 0.f;
;           if (hasln) { vg = *(const GAS float*)(pg + cL); vb = *(const GAS float*)(pb + cL); }
;           if (haszh) vt = *(const GAS float*)(tg + cL);
; template <class Epi>
; __device__ __forceinline__ void gemm_phase(LAS unsigned char* lds, const Gemm g0, const StaticOrder& S, const Epi& E) {
;     ...
;             PG8_LDA(At, 1, 1); PG8_STAGE(PG8_SA(1, 0), a3, voffA);
;             PG8_BAR; PG8_WAIT_L(0); PG8_MMA(1, 0, At, B0); PG8_BAR; PG8_SCHED;
;             PG8_STAGE(PG8_SB(1, 1), b3 + hstep, voffB);
;             PG8_WAIT_V(6); PG8_BAR; PG8_MMA(1, 1, At, B1); PG8_BAR;
;         }
	ds_read_b128 v[146:149], v210 offset:49152
	ds_read_b128 v[150:153], v210 offset:50176
	ds_read_b128 v[154:157], v210 offset:51200
	ds_read_b128 v[158:161], v210 offset:52224
	ds_read_b128 v[188:191], v210 offset:53248
	ds_read_b128 v[192:195], v210 offset:54272
	ds_read_b128 v[196:199], v210 offset:55296
	ds_read_b128 v[200:203], v210 offset:56320
	global_load_lds_dwordx4 v[162:163], off
	v_lshl_add_u64 v[162:163], v[172:173], 0, s[64:65]
	s_mov_b32 m0, s29
	s_nop 0
	global_load_lds_dwordx4 v[162:163], off
	s_barrier
	s_waitcnt lgkmcnt(0)
	v_mfma_f32_16x16x32_f16 v[62:65], v[122:125], v[146:149], v[62:65]
	v_mfma_f32_16x16x32_f16 v[58:61], v[138:141], v[146:149], v[58:61]
	v_mfma_f32_16x16x32_f16 v[46:49], v[122:125], v[154:157], v[46:49]
	v_mfma_f32_16x16x32_f16 v[42:45], v[138:141], v[154:157], v[42:45]
	v_mfma_f32_16x16x32_f16 v[30:33], v[122:125], v[188:191], v[30:33]
	v_mfma_f32_16x16x32_f16 v[26:29], v[138:141], v[188:191], v[26:29]
	v_mfma_f32_16x16x32_f16 v[14:17], v[122:125], v[196:199], v[14:17]
	v_mfma_f32_16x16x32_f16 v[10:13], v[138:141], v[196:199], v[10:13]
	v_mfma_f32_16x16x32_f16 v[62:65], v[126:129], v[150:153], v[62:65]
	v_mfma_f32_16x16x32_f16 v[58:61], v[142:145], v[150:153], v[58:61]
	v_mfma_f32_16x16x32_f16 v[46:49], v[126:129], v[158:161], v[46:49]
	v_mfma_f32_16x16x32_f16 v[42:45], v[142:145], v[158:161], v[42:45]
	v_mfma_f32_16x16x32_f16 v[30:33], v[126:129], v[192:195], v[30:33]
	v_mfma_f32_16x16x32_f16 v[26:29], v[142:145], v[192:195], v[26:29]
	v_mfma_f32_16x16x32_f16 v[14:17], v[126:129], v[200:203], v[14:17]
	v_mfma_f32_16x16x32_f16 v[10:13], v[142:145], v[200:203], v[10:13]
	s_barrier
	s_add_u32 s48, s48, 0x80080
	s_addc_u32 s49, s49, 0
	s_add_i32 s23, s50, s75
	s_mov_b32 m0, s23
	s_nop 0
	global_load_lds_dwordx4 v178, s[48:49]
	s_add_i32 m0, s23, 0x2000
	s_nop 0
	global_load_lds_dwordx4 v174, s[48:49]
	s_waitcnt vmcnt(6)
	s_barrier
	v_mfma_f32_16x16x32_f16 v[54:57], v[212:215], v[146:149], v[54:57]
	v_mfma_f32_16x16x32_f16 v[50:53], v[238:241], v[146:149], v[50:53]
	v_mfma_f32_16x16x32_f16 v[38:41], v[212:215], v[154:157], v[38:41]
	v_mfma_f32_16x16x32_f16 v[34:37], v[238:241], v[154:157], v[34:37]
	v_mfma_f32_16x16x32_f16 v[22:25], v[212:215], v[188:191], v[22:25]
	v_mfma_f32_16x16x32_f16 v[18:21], v[238:241], v[188:191], v[18:21]
	v_mfma_f32_16x16x32_f16 v[6:9], v[212:215], v[196:199], v[6:9]
	v_mfma_f32_16x16x32_f16 v[2:5], v[238:241], v[196:199], v[2:5]
	v_mfma_f32_16x16x32_f16 v[54:57], v[234:237], v[150:153], v[54:57]
	v_mfma_f32_16x16x32_f16 v[50:53], v[242:245], v[150:153], v[50:53]
	v_mfma_f32_16x16x32_f16 v[38:41], v[234:237], v[158:161], v[38:41]
	v_mfma_f32_16x16x32_f16 v[34:37], v[242:245], v[158:161], v[34:37]
	v_mfma_f32_16x16x32_f16 v[22:25], v[234:237], v[192:195], v[22:25]
	v_mfma_f32_16x16x32_f16 v[18:21], v[242:245], v[192:195], v[18:21]
	v_mfma_f32_16x16x32_f16 v[6:9], v[234:237], v[200:203], v[6:9]
	v_mfma_f32_16x16x32_f16 v[2:5], v[242:245], v[200:203], v[2:5]
	s_add_i32 s22, s22, 2
	s_add_u32 vcc_lo, vcc_lo, 0x100
	s_addc_u32 vcc_hi, vcc_hi, 0
	s_add_u32 s12, s12, 0x100
	s_addc_u32 s13, s13, 0
	s_cmp_gt_u32 s22, 29
	s_barrier
	s_cbranch_scc0 .LBB0_512
	s_lshl_b32 s12, s83, 8
	s_or_b32 s15, s12, s31
	v_add_u32_e32 v122, s15, v206
	v_cndmask_b32_e64 v124, 0, 1, s[44:45]
	v_ashrrev_i32_e32 v123, 31, v122
	v_mov_b32_e32 v196, 0
	v_cmp_ne_u32_e64 s[12:13], 1, v124
	s_andn2_b64 vcc, exec, s[44:45]
	v_mov_b32_e32 v124, 0
	v_mov_b32_e32 v125, 0
	s_cbranch_vccnz .LBB0_515
	v_lshlrev_b64 v[124:125], 2, v[122:123]
	v_lshl_add_u64 v[126:127], s[80:81], 0, v[124:125]
	v_lshl_add_u64 v[124:125], s[58:59], 0, v[124:125]
	global_load_dword v125, v[124:125], off
	s_nop 0
	global_load_dword v124, v[126:127], off

;     __device__ __forceinline__ void prefetch(const Unit& u, int wr, int wc, int lane) const { lnfold_prefetch(vl, stats, gW, bW, u, wr, wc, lane); }
;     __device__ __forceinline__ void prefetch(const Unit& u, int wr, int wc, int lane) const { lnfold_prefetch(vl, stats, gW, bW, u, wr, wc, lane); }
; #define PG8_STAGE(bufoff, gbase, voff) do { _Pragma("unroll") for (int _i = 0; _i < 2; ++_i) \
;         __builtin_amdgcn_global_load_lds((const unsigned*)((const char*)(gbase) + (voff)[_i]), (LAS unsigned*)(lds + (bufoff) + ldsw + _i * 8192), 16, 0, 0); } while (0)
; #define PG8_LDA(dst, b, h) do { _Pragma("unroll") for (int m = 0; m < 4; ++m) _Pragma("unroll") for (int k = 0; k < 2; ++k) dst[m][k] = *(const LAS f16x8*)(lds + PG8_SA(b, h) + aoff + m * 2048 + k * 1024); } while (0)
; #define PG8_LDB(dst, b, h) do { _Pragma("unroll") for (int n = 0; n < 2; ++n) _Pragma("unroll") for (int k = 0; k < 2; ++k) dst[n][k] = *(const LAS f16x8*)(lds + PG8_SB(b, h) + boff + n * 2048 + k * 1024); } while (0)
; #define PG8_WAIT_V(n) asm volatile("s_waitcnt vmcnt(" #n ")" ::: "memory")
; #define PG8_WAIT_L(n) asm volatile("s_waitcnt lgkmcnt(" #n ")" ::: "memory")
; template <class Epi>
; __device__ __forceinline__ void gemm_phase(LAS unsigned char* lds, const Gemm g0, const StaticOrder& S, const Epi& E) {
;     ...
;         for (int t = 0; t < nt; t += 2) {
;             const bool last = (t == nt - 2);
;             if (Epi::PREF && last) E.prefetch(cur, wr, wc, lane);
;             const char* a1 = cA + (size_t)(t + 1) * kstep;
;             const char* a2 = last ? nA : cA + (size_t)(t + 2) * kstep; const char* b2 = last ? nB : cB + (size_t)(t + 2) * kstep;
;             const char* a3 = a2 + kstep; const char* b3 = b2 + kstep;
;             PG8_LDB(B0, 0, 0); PG8_SCHED; PG8_LDA(At, 0, 0); PG8_STAGE(PG8_SA(1, 1), a1 + hstep, voffA);
;             PG8_WAIT_L(8); PG8_BAR; PG8_WAIT_L(0); PG8_MMA(0, 0, At, B0); PG8_BAR; PG8_SCHED;
;             PG8_LDB(B1, 0, 1); PG8_STAGE(PG8_SB(0, 0), b2, voffB);
;             PG8_BAR; PG8_WAIT_L(0); PG8_MMA(0, 1, At, B1); PG8_BAR;
;             PG8_LDA(At, 0, 1); PG8_STAGE(PG8_SA(0, 0), a2, voffA);
;             PG8_BAR; PG8_WAIT_L(0); PG8_MMA(1, 0, At, B0); PG8_BAR; PG8_SCHED;
;             PG8_STAGE(PG8_SB(0, 1), b2 + hstep, voffB);
;             PG8_WAIT_V(6); PG8_BAR; PG8_MMA(1, 1, At, B1); PG8_BAR;
.LBB0_620:
	s_add_u32 s58, s50, 0xfff80080
	s_addc_u32 s59, s51, -1
	s_and_b64 s[22:23], s[52:53], exec
	s_cselect_b32 s59, s37, s59
	s_cselect_b32 s58, s74, s58
	s_add_i32 s82, 0, 0x10000
	ds_read_b128 v[60:63], v187
	ds_read_b128 v[64:67], v187 offset:1024
	ds_read_b128 v[78:81], v187 offset:2048
	ds_read_b128 v[82:85], v187 offset:3072
	s_and_b64 s[22:23], s[52:53], exec
	s_cselect_b32 s53, s35, s25
	s_cselect_b32 s52, s75, s24
	s_add_i32 m0, s18, 0xc000
	ds_read_b128 v[86:89], v213
	ds_read_b128 v[90:93], v213 offset:1024
	ds_read_b128 v[194:197], v213 offset:2048
	ds_read_b128 v[234:237], v213 offset:3072
	ds_read_b128 v[238:241], v213 offset:4096
	ds_read_b128 v[242:245], v213 offset:5120
	ds_read_b128 v[246:249], v213 offset:6144
	ds_read_b128 v[226:229], v213 offset:7168
	global_load_lds_dwordx4 v184, s[50:51]
	s_add_i32 m0, s18, 0xe000
	s_nop 0
	global_load_lds_dwordx4 v182, s[50:51]
	s_waitcnt lgkmcnt(8)
	s_barrier
	s_waitcnt lgkmcnt(0)
	v_mfma_f32_16x16x32_f16 v[158:161], v[60:63], v[86:89], v[158:161]
	v_mfma_f32_16x16x32_f16 v[150:153], v[78:81], v[86:89], v[150:153]
	v_mfma_f32_16x16x32_f16 v[142:145], v[60:63], v[194:197], v[142:145]
	v_mfma_f32_16x16x32_f16 v[134:137], v[78:81], v[194:197], v[134:137]
	v_mfma_f32_16x16x32_f16 v[126:129], v[60:63], v[238:241], v[126:129]
	v_mfma_f32_16x16x32_f16 v[118:121], v[78:81], v[238:241], v[118:121]
	v_mfma_f32_16x16x32_f16 v[110:113], v[60:63], v[246:249], v[110:113]
	v_mfma_f32_16x16x32_f16 v[102:105], v[78:81], v[246:249], v[102:105]
	v_mfma_f32_16x16x32_f16 v[158:161], v[64:67], v[90:93], v[158:161]
	v_mfma_f32_16x16x32_f16 v[150:153], v[82:85], v[90:93], v[150:153]
	v_mfma_f32_16x16x32_f16 v[142:145], v[64:67], v[234:237], v[142:145]
	v_mfma_f32_16x16x32_f16 v[134:137], v[82:85], v[234:237], v[134:137]
	v_mfma_f32_16x16x32_f16 v[126:129], v[64:67], v[242:245], v[126:129]
	v_mfma_f32_16x16x32_f16 v[118:121], v[82:85], v[242:245], v[118:121]
	v_mfma_f32_16x16x32_f16 v[110:113], v[64:67], v[226:229], v[110:113]
	v_mfma_f32_16x16x32_f16 v[102:105], v[82:85], v[226:229], v[102:105]
	s_barrier
	s_add_i32 s83, 0, 0x14000
	s_add_i32 s22, s82, s5
	s_mov_b32 m0, s22
	ds_read_b128 v[162:165], v187 offset:16384
	ds_read_b128 v[222:225], v187 offset:17408
	ds_read_b128 v[214:217], v187 offset:18432
	ds_read_b128 v[170:173], v187 offset:19456
	global_load_lds_dwordx4 v178, s[52:53]
	s_add_i32 m0, s22, 0x2000
	s_nop 0
	global_load_lds_dwordx4 v174, s[52:53]
	s_barrier
	s_waitcnt lgkmcnt(0)
	v_mfma_f32_16x16x32_f16 v[154:157], v[162:165], v[86:89], v[154:157]
	v_mfma_f32_16x16x32_f16 v[86:89], v[214:217], v[86:89], v[146:149]
	v_mfma_f32_16x16x32_f16 v[130:133], v[214:217], v[194:197], v[130:133]
	v_mfma_f32_16x16x32_f16 v[122:125], v[162:165], v[238:241], v[122:125]
	v_mfma_f32_16x16x32_f16 v[114:117], v[214:217], v[238:241], v[114:117]
	v_mfma_f32_16x16x32_f16 v[106:109], v[162:165], v[246:249], v[106:109]
	v_mfma_f32_16x16x32_f16 v[98:101], v[214:217], v[246:249], v[98:101]
	v_mfma_f32_16x16x32_f16 v[154:157], v[222:225], v[90:93], v[154:157]
	v_mfma_f32_16x16x32_f16 v[86:89], v[170:173], v[90:93], v[86:89]
	v_mfma_f32_16x16x32_f16 v[90:93], v[162:165], v[194:197], v[138:141]
	v_mfma_f32_16x16x32_f16 v[130:133], v[170:173], v[234:237], v[130:133]
	v_mfma_f32_16x16x32_f16 v[122:125], v[222:225], v[242:245], v[122:125]
	v_mfma_f32_16x16x32_f16 v[114:117], v[170:173], v[242:245], v[114:117]
	v_mfma_f32_16x16x32_f16 v[106:109], v[222:225], v[226:229], v[106:109]
	v_mfma_f32_16x16x32_f16 v[98:101], v[170:173], v[226:229], v[98:101]
	v_mfma_f32_16x16x32_f16 v[90:93], v[222:225], v[234:237], v[90:93]
	s_mov_b32 m0, s18
	s_barrier
	ds_read_b128 v[138:141], v213 offset:16384
	ds_read_b128 v[146:149], v213 offset:17408
	ds_read_b128 v[194:197], v213 offset:18432
	ds_read_b128 v[226:229], v213 offset:19456
	ds_read_b128 v[234:237], v213 offset:20480
	ds_read_b128 v[238:241], v213 offset:21504
	ds_read_b128 v[242:245], v213 offset:22528
	ds_read_b128 v[246:249], v213 offset:23552
	global_load_lds_dwordx4 v180, s[58:59]
	s_mov_b32 m0, s19
	s_nop 0
	global_load_lds_dwordx4 v176, s[58:59]
	s_barrier
	s_waitcnt lgkmcnt(0)
	v_mfma_f32_16x16x32_f16 v[94:97], v[60:63], v[138:141], v[94:97]
	v_mfma_f32_16x16x32_f16 v[68:71], v[78:81], v[138:141], v[70:73]
	v_mfma_f32_16x16x32_f16 v[46:49], v[60:63], v[194:197], v[46:49]
	v_mfma_f32_16x16x32_f16 v[38:41], v[78:81], v[194:197], v[38:41]
	v_mfma_f32_16x16x32_f16 v[30:33], v[60:63], v[234:237], v[30:33]
	v_mfma_f32_16x16x32_f16 v[22:25], v[78:81], v[234:237], v[22:25]
	v_mfma_f32_16x16x32_f16 v[14:17], v[60:63], v[242:245], v[14:17]
	v_mfma_f32_16x16x32_f16 v[6:9], v[78:81], v[242:245], v[6:9]
	v_mfma_f32_16x16x32_f16 v[94:97], v[64:67], v[146:149], v[94:97]
	v_mfma_f32_16x16x32_f16 v[68:71], v[82:85], v[146:149], v[68:71]
	v_mfma_f32_16x16x32_f16 v[46:49], v[64:67], v[226:229], v[46:49]
	v_mfma_f32_16x16x32_f16 v[38:41], v[82:85], v[226:229], v[38:41]
	v_mfma_f32_16x16x32_f16 v[30:33], v[64:67], v[238:241], v[30:33]
	v_mfma_f32_16x16x32_f16 v[22:25], v[82:85], v[238:241], v[22:25]
	v_mfma_f32_16x16x32_f16 v[14:17], v[64:67], v[246:249], v[14:17]
	v_mfma_f32_16x16x32_f16 v[6:9], v[82:85], v[246:249], v[6:9]
	s_barrier
	s_add_u32 s22, s52, 0x80000
	s_addc_u32 s23, s53, 0
	s_add_i32 s82, s83, s5
	s_mov_b32 m0, s82
	s_nop 0
	global_load_lds_dwordx4 v178, s[22:23]
	s_add_i32 m0, s82, 0x2000
	s_nop 0
	global_load_lds_dwordx4 v174, s[22:23]
	s_waitcnt vmcnt(6)
	s_barrier
; #define PG8_STAGE(bufoff, gbase, voff) do { _Pragma("unroll") for (int _i = 0; _i < 2; ++_i) \
;         __builtin_amdgcn_global_load_lds((const unsigned*)((const char*)(gbase) + (voff)[_i]), (LAS unsigned*)(lds + (bufoff) + ldsw + _i * 8192), 16, 0, 0); } while (0)
; #define PG8_LDA(dst, b, h) do { _Pragma("unroll") for (int m = 0; m < 4; ++m) _Pragma("unroll") for (int k = 0; k < 2; ++k) dst[m][k] = *(const LAS f16x8*)(lds + PG8_SA(b, h) + aoff + m * 2048 + k * 1024); } while (0)
; #define PG8_LDB(dst, b, h) do { _Pragma("unroll") for (int n = 0; n < 2; ++n) _Pragma("unroll") for (int k = 0; k < 2; ++k) dst[n][k] = *(const LAS f16x8*)(lds + PG8_SB(b, h) + boff + n * 2048 + k * 1024); } while (0)
; #define PG8_MMA(ai, bj, At, Bt) do { __builtin_amdgcn_s_setprio(1); _Pragma("unroll") for (int m = 0; m < 4; ++m) _Pragma("unroll") for (int n = 0; n < 2; ++n) _Pragma("unroll") for (int k = 0; k < 2; ++k) \
;         acc[ai][bj][m][n] = __builtin_amdgcn_mfma_f32_16x16x32_f16(Bt[n][k], At[m][k], acc[ai][bj][m][n], 0, 0, 0); __builtin_amdgcn_s_setprio(0); } while (0)
; #define PG8_WAIT_V(n) asm volatile("s_waitcnt vmcnt(" #n ")" ::: "memory")
; #define PG8_WAIT_L(n) asm volatile("s_waitcnt lgkmcnt(" #n ")" ::: "memory")
; #define PG8_BAR __builtin_amdgcn_s_barrier()
; #define PG8_SCHED __builtin_amdgcn_sched_barrier(0)
; template <class Epi>
; __device__ __forceinline__ void gemm_phase(LAS unsigned char* lds, const Gemm g0, const StaticOrder& S, const Epi& E) {
;     ...
;             PG8_WAIT_V(6); PG8_BAR; PG8_MMA(1, 1, At, B1); PG8_BAR;
;             PG8_LDB(B0, 1, 0); PG8_SCHED; PG8_LDA(At, 1, 0); PG8_STAGE(PG8_SA(0, 1), a2 + hstep, voffA);
;             PG8_WAIT_L(8); PG8_BAR; PG8_WAIT_L(0); PG8_MMA(0, 0, At, B0); PG8_BAR; PG8_SCHED;
;             PG8_LDB(B1, 1, 1); PG8_STAGE(PG8_SB(1, 0), b3, voffB);
;             PG8_BAR; PG8_WAIT_L(0); PG8_MMA(0, 1, At, B1); PG8_BAR;
	v_mfma_f32_16x16x32_f16 v[50:53], v[214:217], v[138:141], v[50:53]
	v_mfma_f32_16x16x32_f16 v[42:45], v[162:165], v[194:197], v[42:45]
	v_mfma_f32_16x16x32_f16 v[34:37], v[214:217], v[194:197], v[34:37]
	v_mfma_f32_16x16x32_f16 v[26:29], v[162:165], v[234:237], v[26:29]
	v_mfma_f32_16x16x32_f16 v[18:21], v[214:217], v[234:237], v[18:21]
	v_mfma_f32_16x16x32_f16 v[10:13], v[162:165], v[242:245], v[10:13]
	v_mfma_f32_16x16x32_f16 v[2:5], v[214:217], v[242:245], v[2:5]
	v_mfma_f32_16x16x32_f16 v[60:63], v[162:165], v[138:141], v[74:77]
	v_mfma_f32_16x16x32_f16 v[50:53], v[170:173], v[146:149], v[50:53]
	v_mfma_f32_16x16x32_f16 v[42:45], v[222:225], v[226:229], v[42:45]
	v_mfma_f32_16x16x32_f16 v[34:37], v[170:173], v[226:229], v[34:37]
	v_mfma_f32_16x16x32_f16 v[26:29], v[222:225], v[238:241], v[26:29]
	v_mfma_f32_16x16x32_f16 v[18:21], v[170:173], v[238:241], v[18:21]
	v_mfma_f32_16x16x32_f16 v[10:13], v[222:225], v[246:249], v[10:13]
	v_mfma_f32_16x16x32_f16 v[2:5], v[170:173], v[246:249], v[2:5]
	v_mfma_f32_16x16x32_f16 v[60:63], v[222:225], v[146:149], v[60:63]
	s_add_i32 s82, 0, 0x18000
	s_barrier
	ds_read_b128 v[64:67], v187 offset:32768
	ds_read_b128 v[74:77], v187 offset:33792
	ds_read_b128 v[78:81], v187 offset:34816
	ds_read_b128 v[82:85], v187 offset:35840
	s_add_u32 s22, s58, 0x80000
	s_addc_u32 s23, s59, 0
	s_mov_b32 m0, s28
	ds_read_b128 v[138:141], v213 offset:32768
	ds_read_b128 v[146:149], v213 offset:33792
	ds_read_b128 v[162:165], v213 offset:34816
	ds_read_b128 v[170:173], v213 offset:35840
	ds_read_b128 v[194:197], v213 offset:36864
	ds_read_b128 v[214:217], v213 offset:37888
	ds_read_b128 v[222:225], v213 offset:38912
	ds_read_b128 v[226:229], v213 offset:39936
	global_load_lds_dwordx4 v180, s[22:23]
	s_mov_b32 m0, s29
	s_nop 0
	global_load_lds_dwordx4 v176, s[22:23]
	s_waitcnt lgkmcnt(8)
	s_barrier
	s_waitcnt lgkmcnt(0)
	v_mfma_f32_16x16x32_f16 v[158:161], v[64:67], v[138:141], v[158:161]
	v_mfma_f32_16x16x32_f16 v[150:153], v[78:81], v[138:141], v[150:153]
	v_mfma_f32_16x16x32_f16 v[142:145], v[64:67], v[162:165], v[142:145]
	v_mfma_f32_16x16x32_f16 v[134:137], v[78:81], v[162:165], v[134:137]
	v_mfma_f32_16x16x32_f16 v[126:129], v[64:67], v[194:197], v[126:129]
	v_mfma_f32_16x16x32_f16 v[118:121], v[78:81], v[194:197], v[118:121]
	v_mfma_f32_16x16x32_f16 v[110:113], v[64:67], v[222:225], v[110:113]
	v_mfma_f32_16x16x32_f16 v[102:105], v[78:81], v[222:225], v[102:105]
	v_mfma_f32_16x16x32_f16 v[158:161], v[74:77], v[146:149], v[158:161]
	v_mfma_f32_16x16x32_f16 v[150:153], v[82:85], v[146:149], v[150:153]
	v_mfma_f32_16x16x32_f16 v[142:145], v[74:77], v[170:173], v[142:145]
	v_mfma_f32_16x16x32_f16 v[134:137], v[82:85], v[170:173], v[134:137]
	v_mfma_f32_16x16x32_f16 v[126:129], v[74:77], v[214:217], v[126:129]
	v_mfma_f32_16x16x32_f16 v[118:121], v[82:85], v[214:217], v[118:121]
	v_mfma_f32_16x16x32_f16 v[110:113], v[74:77], v[226:229], v[110:113]
	v_mfma_f32_16x16x32_f16 v[102:105], v[82:85], v[226:229], v[102:105]
	s_barrier
	s_add_i32 s83, 0, 0x1c000
	s_add_i32 s22, s82, s5
	ds_read_b128 v[234:237], v187 offset:49152
	ds_read_b128 v[238:241], v187 offset:50176
	ds_read_b128 v[242:245], v187 offset:51200
	ds_read_b128 v[246:249], v187 offset:52224
	s_mov_b32 m0, s22
	s_nop 0
	global_load_lds_dwordx4 v186, s[52:53]
	s_add_i32 m0, s22, 0x2000
	s_nop 0
	global_load_lds_dwordx4 v190, s[52:53]
	s_barrier
; #define PG8_STAGE(bufoff, gbase, voff) do { _Pragma("unroll") for (int _i = 0; _i < 2; ++_i) \
;         __builtin_amdgcn_global_load_lds((const unsigned*)((const char*)(gbase) + (voff)[_i]), (LAS unsigned*)(lds + (bufoff) + ldsw + _i * 8192), 16, 0, 0); } while (0)
; #define PG8_LDA(dst, b, h) do { _Pragma("unroll") for (int m = 0; m < 4; ++m) _Pragma("unroll") for (int k = 0; k < 2; ++k) dst[m][k] = *(const LAS f16x8*)(lds + PG8_SA(b, h) + aoff + m * 2048 + k * 1024); } while (0)
; #define PG8_MMA(ai, bj, At, Bt) do { __builtin_amdgcn_s_setprio(1); _Pragma("unroll") for (int m = 0; m < 4; ++m) _Pragma("unroll") for (int n = 0; n < 2; ++n) _Pragma("unroll") for (int k = 0; k < 2; ++k) \
;         acc[ai][bj][m][n] = __builtin_amdgcn_mfma_f32_16x16x32_f16(Bt[n][k], At[m][k], acc[ai][bj][m][n], 0, 0, 0); __builtin_amdgcn_s_setprio(0); } while (0)
; #define PG8_WAIT_V(n) asm volatile("s_waitcnt vmcnt(" #n ")" ::: "memory")
; #define PG8_WAIT_L(n) asm volatile("s_waitcnt lgkmcnt(" #n ")" ::: "memory")
; #define PG8_BAR __builtin_amdgcn_s_barrier()
; #define PG8_SCHED __builtin_amdgcn_sched_barrier(0)
; template <class Epi>
; __device__ __forceinline__ void gemm_phase(LAS unsigned char* lds, const Gemm g0, const StaticOrder& S, const Epi& E) {
;     ...
;             PG8_BAR; PG8_WAIT_L(0); PG8_MMA(0, 1, At, B1); PG8_BAR;
;             PG8_LDA(At, 1, 1); PG8_STAGE(PG8_SA(1, 0), a3, voffA);
;             PG8_BAR; PG8_WAIT_L(0); PG8_MMA(1, 0, At, B0); PG8_BAR; PG8_SCHED;
;             PG8_STAGE(PG8_SB(1, 1), b3 + hstep, voffB);
;             PG8_WAIT_V(6); PG8_BAR; PG8_MMA(1, 1, At, B1); PG8_BAR;
;         }
	s_waitcnt lgkmcnt(0)
	v_mfma_f32_16x16x32_f16 v[154:157], v[234:237], v[138:141], v[154:157]
	v_mfma_f32_16x16x32_f16 v[86:89], v[242:245], v[138:141], v[86:89]
	v_mfma_f32_16x16x32_f16 v[154:157], v[238:241], v[146:149], v[154:157]
	v_mfma_f32_16x16x32_f16 v[146:149], v[246:249], v[146:149], v[86:89]
	v_mfma_f32_16x16x32_f16 v[86:89], v[234:237], v[162:165], v[90:93]
	v_mfma_f32_16x16x32_f16 v[138:141], v[238:241], v[170:173], v[86:89]
	v_mfma_f32_16x16x32_f16 v[86:89], v[242:245], v[162:165], v[130:133]
	v_mfma_f32_16x16x32_f16 v[130:133], v[246:249], v[170:173], v[86:89]
	v_mfma_f32_16x16x32_f16 v[86:89], v[234:237], v[194:197], v[122:125]
	v_mfma_f32_16x16x32_f16 v[122:125], v[238:241], v[214:217], v[86:89]
	v_mfma_f32_16x16x32_f16 v[86:89], v[242:245], v[194:197], v[114:117]
	v_mfma_f32_16x16x32_f16 v[114:117], v[246:249], v[214:217], v[86:89]
	v_mfma_f32_16x16x32_f16 v[86:89], v[234:237], v[222:225], v[106:109]
	v_mfma_f32_16x16x32_f16 v[106:109], v[238:241], v[226:229], v[86:89]
	v_mfma_f32_16x16x32_f16 v[86:89], v[242:245], v[222:225], v[98:101]
	v_mfma_f32_16x16x32_f16 v[98:101], v[246:249], v[226:229], v[86:89]
	s_mov_b32 m0, s31
	s_barrier
	s_nop 2
	ds_read_b128 v[86:89], v213 offset:49152
	ds_read_b128 v[90:93], v213 offset:50176
	ds_read_b128 v[162:165], v213 offset:51200
	ds_read_b128 v[170:173], v213 offset:52224
	ds_read_b128 v[194:197], v213 offset:53248
	ds_read_b128 v[214:217], v213 offset:54272
	ds_read_b128 v[222:225], v213 offset:55296
	ds_read_b128 v[226:229], v213 offset:56320
	global_load_lds_dwordx4 v198, s[58:59]
	s_mov_b32 m0, s61
	s_nop 0
	global_load_lds_dwordx4 v202, s[58:59]
	s_barrier
	s_waitcnt lgkmcnt(0)
	v_mfma_f32_16x16x32_f16 v[94:97], v[64:67], v[86:89], v[94:97]
	v_mfma_f32_16x16x32_f16 v[68:71], v[78:81], v[86:89], v[68:71]
	v_mfma_f32_16x16x32_f16 v[46:49], v[64:67], v[162:165], v[46:49]
	v_mfma_f32_16x16x32_f16 v[38:41], v[78:81], v[162:165], v[38:41]
	v_mfma_f32_16x16x32_f16 v[30:33], v[64:67], v[194:197], v[30:33]
	v_mfma_f32_16x16x32_f16 v[22:25], v[78:81], v[194:197], v[22:25]
	v_mfma_f32_16x16x32_f16 v[14:17], v[64:67], v[222:225], v[14:17]
	v_mfma_f32_16x16x32_f16 v[6:9], v[78:81], v[222:225], v[6:9]
	v_mfma_f32_16x16x32_f16 v[94:97], v[74:77], v[90:93], v[94:97]
	v_mfma_f32_16x16x32_f16 v[70:73], v[82:85], v[90:93], v[68:71]
	v_mfma_f32_16x16x32_f16 v[46:49], v[74:77], v[170:173], v[46:49]
	v_mfma_f32_16x16x32_f16 v[38:41], v[82:85], v[170:173], v[38:41]
	v_mfma_f32_16x16x32_f16 v[30:33], v[74:77], v[214:217], v[30:33]
	v_mfma_f32_16x16x32_f16 v[22:25], v[82:85], v[214:217], v[22:25]
	v_mfma_f32_16x16x32_f16 v[14:17], v[74:77], v[226:229], v[14:17]
	v_mfma_f32_16x16x32_f16 v[6:9], v[82:85], v[226:229], v[6:9]
	s_barrier
	s_add_u32 s22, s52, 0x80080
	s_addc_u32 s23, s53, 0
	s_add_i32 s52, s83, s5
	s_mov_b32 m0, s52
	s_nop 0
	global_load_lds_dwordx4 v178, s[22:23]
	s_add_i32 m0, s52, 0x2000
	s_nop 0
	global_load_lds_dwordx4 v174, s[22:23]
	s_waitcnt vmcnt(6)
	s_barrier
	v_mfma_f32_16x16x32_f16 v[60:63], v[234:237], v[86:89], v[60:63]
	v_mfma_f32_16x16x32_f16 v[50:53], v[242:245], v[86:89], v[50:53]
	v_mfma_f32_16x16x32_f16 v[42:45], v[234:237], v[162:165], v[42:45]
	v_mfma_f32_16x16x32_f16 v[34:37], v[242:245], v[162:165], v[34:37]
	v_mfma_f32_16x16x32_f16 v[26:29], v[234:237], v[194:197], v[26:29]
	v_mfma_f32_16x16x32_f16 v[18:21], v[242:245], v[194:197], v[18:21]
	v_mfma_f32_16x16x32_f16 v[10:13], v[234:237], v[222:225], v[10:13]
	v_mfma_f32_16x16x32_f16 v[2:5], v[242:245], v[222:225], v[2:5]
	v_mfma_f32_16x16x32_f16 v[74:77], v[238:241], v[90:93], v[60:63]
	v_mfma_f32_16x16x32_f16 v[50:53], v[246:249], v[90:93], v[50:53]
	v_mfma_f32_16x16x32_f16 v[42:45], v[238:241], v[170:173], v[42:45]
	v_mfma_f32_16x16x32_f16 v[34:37], v[246:249], v[170:173], v[34:37]
	v_mfma_f32_16x16x32_f16 v[26:29], v[238:241], v[214:217], v[26:29]
	v_mfma_f32_16x16x32_f16 v[18:21], v[246:249], v[214:217], v[18:21]
	v_mfma_f32_16x16x32_f16 v[10:13], v[238:241], v[226:229], v[10:13]
	v_mfma_f32_16x16x32_f16 v[2:5], v[246:249], v[226:229], v[2:5]
	s_add_i32 s81, s81, 2
	s_add_u32 s24, s24, 0x100
	s_addc_u32 s25, s25, 0
	s_add_u32 s50, s50, 0x100
	s_addc_u32 s51, s51, 0
	s_cmp_gt_u32 s81, 29
	s_barrier
	s_cbranch_scc1 .LBB0_616

;     __device__ __forceinline__ void prefetch(const Unit& u, int wr, int wc, int lane) const { lnfold_prefetch(vl, stats, gW, bW, u, wr, wc, lane); }
;     __device__ __forceinline__ void prefetch(const Unit& u, int wr, int wc, int lane) const { lnfold_prefetch(vl, stats, gW, bW, u, wr, wc, lane); }
; #define PG8_STAGE(bufoff, gbase, voff) do { _Pragma("unroll") for (int _i = 0; _i < 2; ++_i) \
;         __builtin_amdgcn_global_load_lds((const unsigned*)((const char*)(gbase) + (voff)[_i]), (LAS unsigned*)(lds + (bufoff) + ldsw + _i * 8192), 16, 0, 0); } while (0)
; #define PG8_LDA(dst, b, h) do { _Pragma("unroll") for (int m = 0; m < 4; ++m) _Pragma("unroll") for (int k = 0; k < 2; ++k) dst[m][k] = *(const LAS f16x8*)(lds + PG8_SA(b, h) + aoff + m * 2048 + k * 1024); } while (0)
; #define PG8_LDB(dst, b, h) do { _Pragma("unroll") for (int n = 0; n < 2; ++n) _Pragma("unroll") for (int k = 0; k < 2; ++k) dst[n][k] = *(const LAS f16x8*)(lds + PG8_SB(b, h) + boff + n * 2048 + k * 1024); } while (0)
; #define PG8_WAIT_V(n) asm volatile("s_waitcnt vmcnt(" #n ")" ::: "memory")
; #define PG8_WAIT_L(n) asm volatile("s_waitcnt lgkmcnt(" #n ")" ::: "memory")
; template <class Epi>
; __device__ __forceinline__ void gemm_phase(LAS unsigned char* lds, const Gemm g0, const StaticOrder& S, const Epi& E) {
;     ...
;         for (int t = 0; t < nt; t += 2) {
;             const bool last = (t == nt - 2);
;             if (Epi::PREF && last) E.prefetch(cur, wr, wc, lane);
;             const char* a1 = cA + (size_t)(t + 1) * kstep;
;             const char* a2 = last ? nA : cA + (size_t)(t + 2) * kstep; const char* b2 = last ? nB : cB + (size_t)(t + 2) * kstep;
;             const char* a3 = a2 + kstep; const char* b3 = b2 + kstep;
;             PG8_LDB(B0, 0, 0); PG8_SCHED; PG8_LDA(At, 0, 0); PG8_STAGE(PG8_SA(1, 1), a1 + hstep, voffA);
;             PG8_WAIT_L(8); PG8_BAR; PG8_WAIT_L(0); PG8_MMA(0, 0, At, B0); PG8_BAR; PG8_SCHED;
;             PG8_LDB(B1, 0, 1); PG8_STAGE(PG8_SB(0, 0), b2, voffB);
;             PG8_BAR; PG8_WAIT_L(0); PG8_MMA(0, 1, At, B1); PG8_BAR;
;             PG8_LDA(At, 0, 1); PG8_STAGE(PG8_SA(0, 0), a2, voffA);
;             PG8_BAR; PG8_WAIT_L(0); PG8_MMA(1, 0, At, B0); PG8_BAR; PG8_SCHED;
;             PG8_STAGE(PG8_SB(0, 1), b2 + hstep, voffB);
;             PG8_WAIT_V(6); PG8_BAR; PG8_MMA(1, 1, At, B1); PG8_BAR;
.LBB0_672:
	s_add_u32 s10, s12, 0x100
	s_addc_u32 s11, s13, 0
	s_add_i32 s23, 0, 0x10000
	ds_read_b128 v[130:133], v201
	ds_read_b128 v[134:137], v201 offset:1024
	ds_read_b128 v[138:141], v201 offset:2048
	ds_read_b128 v[142:145], v201 offset:3072
	s_cmpk_eq_i32 s22, 0x54
	s_cselect_b32 s81, s1, s11
	s_cselect_b32 s80, s0, s10
	s_cselect_b32 s63, s59, s25
	s_cselect_b32 s62, s58, s24
	s_add_i32 m0, s28, 0xc000
	ds_read_b128 v[146:149], v208
	ds_read_b128 v[150:153], v208 offset:1024
	ds_read_b128 v[154:157], v208 offset:2048
	ds_read_b128 v[162:165], v208 offset:3072
	ds_read_b128 v[170:173], v208 offset:4096
	ds_read_b128 v[184:187], v208 offset:5120
	ds_read_b128 v[188:191], v208 offset:6144
	ds_read_b128 v[192:195], v208 offset:7168
	global_load_lds_dwordx4 v182, s[12:13]
	s_add_i32 m0, s28, 0xe000
	s_nop 0
	global_load_lds_dwordx4 v180, s[12:13]
	s_waitcnt lgkmcnt(8)
	s_barrier
	s_waitcnt lgkmcnt(0)
	v_mfma_f32_16x16x32_f16 v[126:129], v[130:133], v[146:149], v[126:129]
	v_mfma_f32_16x16x32_f16 v[122:125], v[138:141], v[146:149], v[122:125]
	v_mfma_f32_16x16x32_f16 v[110:113], v[130:133], v[154:157], v[110:113]
	v_mfma_f32_16x16x32_f16 v[106:109], v[138:141], v[154:157], v[106:109]
	v_mfma_f32_16x16x32_f16 v[94:97], v[130:133], v[170:173], v[94:97]
	v_mfma_f32_16x16x32_f16 v[90:93], v[138:141], v[170:173], v[90:93]
	v_mfma_f32_16x16x32_f16 v[78:81], v[130:133], v[188:191], v[78:81]
	v_mfma_f32_16x16x32_f16 v[74:77], v[138:141], v[188:191], v[74:77]
	v_mfma_f32_16x16x32_f16 v[126:129], v[134:137], v[150:153], v[126:129]
	v_mfma_f32_16x16x32_f16 v[122:125], v[142:145], v[150:153], v[122:125]
	v_mfma_f32_16x16x32_f16 v[110:113], v[134:137], v[162:165], v[110:113]
	v_mfma_f32_16x16x32_f16 v[106:109], v[142:145], v[162:165], v[106:109]
	v_mfma_f32_16x16x32_f16 v[94:97], v[134:137], v[184:187], v[94:97]
	v_mfma_f32_16x16x32_f16 v[90:93], v[142:145], v[184:187], v[90:93]
	v_mfma_f32_16x16x32_f16 v[78:81], v[134:137], v[192:195], v[78:81]
	v_mfma_f32_16x16x32_f16 v[74:77], v[142:145], v[192:195], v[74:77]
	s_barrier
	s_add_i32 s90, 0, 0x14000
	s_add_i32 s12, s23, s19
	ds_read_b128 v[196:199], v201 offset:16384
	ds_read_b128 v[210:213], v201 offset:17408
	ds_read_b128 v[214:217], v201 offset:18432
	s_mov_b32 m0, s12
	ds_read_b128 v[222:225], v201 offset:19456
	global_load_lds_dwordx4 v174, s[62:63]
	s_add_i32 m0, s12, 0x2000
	s_nop 0
	global_load_lds_dwordx4 v158, s[62:63]
	s_barrier
	s_waitcnt lgkmcnt(0)
	v_mfma_f32_16x16x32_f16 v[118:121], v[196:199], v[146:149], v[118:121]
	v_mfma_f32_16x16x32_f16 v[114:117], v[214:217], v[146:149], v[114:117]
	v_mfma_f32_16x16x32_f16 v[102:105], v[196:199], v[154:157], v[102:105]
	v_mfma_f32_16x16x32_f16 v[98:101], v[214:217], v[154:157], v[98:101]
	v_mfma_f32_16x16x32_f16 v[86:89], v[196:199], v[170:173], v[86:89]
	v_mfma_f32_16x16x32_f16 v[82:85], v[214:217], v[170:173], v[82:85]
	v_mfma_f32_16x16x32_f16 v[70:73], v[196:199], v[188:191], v[70:73]
	v_mfma_f32_16x16x32_f16 v[66:69], v[214:217], v[188:191], v[66:69]
	v_mfma_f32_16x16x32_f16 v[118:121], v[210:213], v[150:153], v[118:121]
	v_mfma_f32_16x16x32_f16 v[114:117], v[222:225], v[150:153], v[114:117]
	v_mfma_f32_16x16x32_f16 v[102:105], v[210:213], v[162:165], v[102:105]
	v_mfma_f32_16x16x32_f16 v[98:101], v[222:225], v[162:165], v[98:101]
	v_mfma_f32_16x16x32_f16 v[86:89], v[210:213], v[184:187], v[86:89]
	v_mfma_f32_16x16x32_f16 v[82:85], v[222:225], v[184:187], v[82:85]
	v_mfma_f32_16x16x32_f16 v[70:73], v[210:213], v[192:195], v[70:73]
	v_mfma_f32_16x16x32_f16 v[66:69], v[222:225], v[192:195], v[66:69]
	s_mov_b32 m0, s28
	s_barrier
	ds_read_b128 v[146:149], v208 offset:16384
	ds_read_b128 v[150:153], v208 offset:17408
	ds_read_b128 v[154:157], v208 offset:18432
	ds_read_b128 v[162:165], v208 offset:19456
	ds_read_b128 v[170:173], v208 offset:20480
	ds_read_b128 v[184:187], v208 offset:21504
	ds_read_b128 v[188:191], v208 offset:22528
	ds_read_b128 v[192:195], v208 offset:23552
	global_load_lds_dwordx4 v176, s[80:81]
	s_mov_b32 m0, s29
	s_nop 0
	global_load_lds_dwordx4 v160, s[80:81]
	s_barrier
	s_waitcnt lgkmcnt(0)
	v_mfma_f32_16x16x32_f16 v[62:65], v[130:133], v[146:149], v[62:65]
	v_mfma_f32_16x16x32_f16 v[58:61], v[138:141], v[146:149], v[58:61]
	v_mfma_f32_16x16x32_f16 v[46:49], v[130:133], v[154:157], v[46:49]
	v_mfma_f32_16x16x32_f16 v[42:45], v[138:141], v[154:157], v[42:45]
	v_mfma_f32_16x16x32_f16 v[30:33], v[130:133], v[170:173], v[30:33]
	v_mfma_f32_16x16x32_f16 v[26:29], v[138:141], v[170:173], v[26:29]
	v_mfma_f32_16x16x32_f16 v[14:17], v[130:133], v[188:191], v[14:17]
	v_mfma_f32_16x16x32_f16 v[10:13], v[138:141], v[188:191], v[10:13]
	v_mfma_f32_16x16x32_f16 v[62:65], v[134:137], v[150:153], v[62:65]
	v_mfma_f32_16x16x32_f16 v[58:61], v[142:145], v[150:153], v[58:61]
	v_mfma_f32_16x16x32_f16 v[46:49], v[134:137], v[162:165], v[46:49]
	v_mfma_f32_16x16x32_f16 v[42:45], v[142:145], v[162:165], v[42:45]
	v_mfma_f32_16x16x32_f16 v[30:33], v[134:137], v[184:187], v[30:33]
	v_mfma_f32_16x16x32_f16 v[26:29], v[142:145], v[184:187], v[26:29]
	v_mfma_f32_16x16x32_f16 v[14:17], v[134:137], v[192:195], v[14:17]
	v_mfma_f32_16x16x32_f16 v[10:13], v[142:145], v[192:195], v[10:13]
	s_barrier
	s_add_u32 s12, s62, 0x160000
	s_addc_u32 s13, s63, 0
	s_add_i32 s23, s90, s19
	s_mov_b32 m0, s23
	s_nop 0
	global_load_lds_dwordx4 v174, s[12:13]
	s_add_i32 m0, s23, 0x2000
	s_nop 0
	global_load_lds_dwordx4 v158, s[12:13]
	s_waitcnt vmcnt(6)
	s_barrier
; #define PG8_STAGE(bufoff, gbase, voff) do { _Pragma("unroll") for (int _i = 0; _i < 2; ++_i) \
;         __builtin_amdgcn_global_load_lds((const unsigned*)((const char*)(gbase) + (voff)[_i]), (LAS unsigned*)(lds + (bufoff) + ldsw + _i * 8192), 16, 0, 0); } while (0)
; #define PG8_LDA(dst, b, h) do { _Pragma("unroll") for (int m = 0; m < 4; ++m) _Pragma("unroll") for (int k = 0; k < 2; ++k) dst[m][k] = *(const LAS f16x8*)(lds + PG8_SA(b, h) + aoff + m * 2048 + k * 1024); } while (0)
; #define PG8_LDB(dst, b, h) do { _Pragma("unroll") for (int n = 0; n < 2; ++n) _Pragma("unroll") for (int k = 0; k < 2; ++k) dst[n][k] = *(const LAS f16x8*)(lds + PG8_SB(b, h) + boff + n * 2048 + k * 1024); } while (0)
; #define PG8_MMA(ai, bj, At, Bt) do { __builtin_amdgcn_s_setprio(1); _Pragma("unroll") for (int m = 0; m < 4; ++m) _Pragma("unroll") for (int n = 0; n < 2; ++n) _Pragma("unroll") for (int k = 0; k < 2; ++k) \
;         acc[ai][bj][m][n] = __builtin_amdgcn_mfma_f32_16x16x32_f16(Bt[n][k], At[m][k], acc[ai][bj][m][n], 0, 0, 0); __builtin_amdgcn_s_setprio(0); } while (0)
; #define PG8_WAIT_V(n) asm volatile("s_waitcnt vmcnt(" #n ")" ::: "memory")
; #define PG8_WAIT_L(n) asm volatile("s_waitcnt lgkmcnt(" #n ")" ::: "memory")
; #define PG8_BAR __builtin_amdgcn_s_barrier()
; #define PG8_SCHED __builtin_amdgcn_sched_barrier(0)
; template <class Epi>
; __device__ __forceinline__ void gemm_phase(LAS unsigned char* lds, const Gemm g0, const StaticOrder& S, const Epi& E) {
;     ...
;             PG8_WAIT_V(6); PG8_BAR; PG8_MMA(1, 1, At, B1); PG8_BAR;
;             PG8_LDB(B0, 1, 0); PG8_SCHED; PG8_LDA(At, 1, 0); PG8_STAGE(PG8_SA(0, 1), a2 + hstep, voffA);
;             PG8_WAIT_L(8); PG8_BAR; PG8_WAIT_L(0); PG8_MMA(0, 0, At, B0); PG8_BAR; PG8_SCHED;
;             PG8_LDB(B1, 1, 1); PG8_STAGE(PG8_SB(1, 0), b3, voffB);
;             PG8_BAR; PG8_WAIT_L(0); PG8_MMA(0, 1, At, B1); PG8_BAR;
;             PG8_LDA(At, 1, 1); PG8_STAGE(PG8_SA(1, 0), a3, voffA);
	v_mfma_f32_16x16x32_f16 v[54:57], v[196:199], v[146:149], v[54:57]
	v_mfma_f32_16x16x32_f16 v[50:53], v[214:217], v[146:149], v[50:53]
	v_mfma_f32_16x16x32_f16 v[38:41], v[196:199], v[154:157], v[38:41]
	v_mfma_f32_16x16x32_f16 v[34:37], v[214:217], v[154:157], v[34:37]
	v_mfma_f32_16x16x32_f16 v[22:25], v[196:199], v[170:173], v[22:25]
	v_mfma_f32_16x16x32_f16 v[18:21], v[214:217], v[170:173], v[18:21]
	v_mfma_f32_16x16x32_f16 v[6:9], v[196:199], v[188:191], v[6:9]
	v_mfma_f32_16x16x32_f16 v[2:5], v[214:217], v[188:191], v[2:5]
	v_mfma_f32_16x16x32_f16 v[54:57], v[210:213], v[150:153], v[54:57]
	v_mfma_f32_16x16x32_f16 v[50:53], v[222:225], v[150:153], v[50:53]
	v_mfma_f32_16x16x32_f16 v[38:41], v[210:213], v[162:165], v[38:41]
	v_mfma_f32_16x16x32_f16 v[34:37], v[222:225], v[162:165], v[34:37]
	v_mfma_f32_16x16x32_f16 v[22:25], v[210:213], v[184:187], v[22:25]
	v_mfma_f32_16x16x32_f16 v[18:21], v[222:225], v[184:187], v[18:21]
	v_mfma_f32_16x16x32_f16 v[6:9], v[210:213], v[192:195], v[6:9]
	v_mfma_f32_16x16x32_f16 v[2:5], v[222:225], v[192:195], v[2:5]
	s_add_i32 s23, 0, 0x18000
	s_barrier
	ds_read_b128 v[130:133], v201 offset:32768
	ds_read_b128 v[134:137], v201 offset:33792
	ds_read_b128 v[138:141], v201 offset:34816
	ds_read_b128 v[142:145], v201 offset:35840
	s_add_u32 s12, s80, 0x160000
	s_addc_u32 s13, s81, 0
	s_mov_b32 m0, s31
	ds_read_b128 v[146:149], v208 offset:32768
	ds_read_b128 v[150:153], v208 offset:33792
	ds_read_b128 v[154:157], v208 offset:34816
	ds_read_b128 v[162:165], v208 offset:35840
	ds_read_b128 v[170:173], v208 offset:36864
	ds_read_b128 v[184:187], v208 offset:37888
	ds_read_b128 v[188:191], v208 offset:38912
	ds_read_b128 v[192:195], v208 offset:39936
	global_load_lds_dwordx4 v176, s[12:13]
	s_mov_b32 m0, s61
	s_nop 0
	global_load_lds_dwordx4 v160, s[12:13]
	s_waitcnt lgkmcnt(8)
	s_barrier
	s_waitcnt lgkmcnt(0)
	v_mfma_f32_16x16x32_f16 v[126:129], v[130:133], v[146:149], v[126:129]
	v_mfma_f32_16x16x32_f16 v[122:125], v[138:141], v[146:149], v[122:125]
	v_mfma_f32_16x16x32_f16 v[110:113], v[130:133], v[154:157], v[110:113]
	v_mfma_f32_16x16x32_f16 v[106:109], v[138:141], v[154:157], v[106:109]
	v_mfma_f32_16x16x32_f16 v[94:97], v[130:133], v[170:173], v[94:97]
	v_mfma_f32_16x16x32_f16 v[90:93], v[138:141], v[170:173], v[90:93]
	v_mfma_f32_16x16x32_f16 v[78:81], v[130:133], v[188:191], v[78:81]
	v_mfma_f32_16x16x32_f16 v[74:77], v[138:141], v[188:191], v[74:77]
	v_mfma_f32_16x16x32_f16 v[126:129], v[134:137], v[150:153], v[126:129]
	v_mfma_f32_16x16x32_f16 v[122:125], v[142:145], v[150:153], v[122:125]
	v_mfma_f32_16x16x32_f16 v[110:113], v[134:137], v[162:165], v[110:113]
	v_mfma_f32_16x16x32_f16 v[106:109], v[142:145], v[162:165], v[106:109]
	v_mfma_f32_16x16x32_f16 v[94:97], v[134:137], v[184:187], v[94:97]
	v_mfma_f32_16x16x32_f16 v[90:93], v[142:145], v[184:187], v[90:93]
	v_mfma_f32_16x16x32_f16 v[78:81], v[134:137], v[192:195], v[78:81]
	v_mfma_f32_16x16x32_f16 v[74:77], v[142:145], v[192:195], v[74:77]
	s_barrier
	s_add_i32 s90, 0, 0x1c000
	s_add_i32 s12, s23, s19
	s_mov_b32 m0, s12
	ds_read_b128 v[196:199], v201 offset:49152
	ds_read_b128 v[210:213], v201 offset:50176
	ds_read_b128 v[214:217], v201 offset:51200
	ds_read_b128 v[222:225], v201 offset:52224
	global_load_lds_dwordx4 v200, s[62:63]
	s_add_i32 m0, s12, 0x2000
	s_nop 0
	global_load_lds_dwordx4 v218, s[62:63]
	s_barrier
	s_waitcnt lgkmcnt(0)
	v_mfma_f32_16x16x32_f16 v[118:121], v[196:199], v[146:149], v[118:121]
	v_mfma_f32_16x16x32_f16 v[114:117], v[214:217], v[146:149], v[114:117]
	v_mfma_f32_16x16x32_f16 v[102:105], v[196:199], v[154:157], v[102:105]
	v_mfma_f32_16x16x32_f16 v[98:101], v[214:217], v[154:157], v[98:101]
	v_mfma_f32_16x16x32_f16 v[86:89], v[196:199], v[170:173], v[86:89]
	v_mfma_f32_16x16x32_f16 v[82:85], v[214:217], v[170:173], v[82:85]
	v_mfma_f32_16x16x32_f16 v[70:73], v[196:199], v[188:191], v[70:73]
	v_mfma_f32_16x16x32_f16 v[66:69], v[214:217], v[188:191], v[66:69]
	v_mfma_f32_16x16x32_f16 v[118:121], v[210:213], v[150:153], v[118:121]
	v_mfma_f32_16x16x32_f16 v[114:117], v[222:225], v[150:153], v[114:117]
	v_mfma_f32_16x16x32_f16 v[102:105], v[210:213], v[162:165], v[102:105]
	v_mfma_f32_16x16x32_f16 v[98:101], v[222:225], v[162:165], v[98:101]
	v_mfma_f32_16x16x32_f16 v[86:89], v[210:213], v[184:187], v[86:89]
	v_mfma_f32_16x16x32_f16 v[82:85], v[222:225], v[184:187], v[82:85]
	v_mfma_f32_16x16x32_f16 v[70:73], v[210:213], v[192:195], v[70:73]
	v_mfma_f32_16x16x32_f16 v[66:69], v[222:225], v[192:195], v[66:69]
	s_mov_b32 m0, s83
	s_barrier
; #define GAS __attribute__((address_space(1)))
; #define PG8_STAGE(bufoff, gbase, voff) do { _Pragma("unroll") for (int _i = 0; _i < 2; ++_i) \
;         __builtin_amdgcn_global_load_lds((const unsigned*)((const char*)(gbase) + (voff)[_i]), (LAS unsigned*)(lds + (bufoff) + ldsw + _i * 8192), 16, 0, 0); } while (0)
; #define PG8_LDA(dst, b, h) do { _Pragma("unroll") for (int m = 0; m < 4; ++m) _Pragma("unroll") for (int k = 0; k < 2; ++k) dst[m][k] = *(const LAS f16x8*)(lds + PG8_SA(b, h) + aoff + m * 2048 + k * 1024); } while (0)
; #define PG8_MMA(ai, bj, At, Bt) do { __builtin_amdgcn_s_setprio(1); _Pragma("unroll") for (int m = 0; m < 4; ++m) _Pragma("unroll") for (int n = 0; n < 2; ++n) _Pragma("unroll") for (int k = 0; k < 2; ++k) \
;         acc[ai][bj][m][n] = __builtin_amdgcn_mfma_f32_16x16x32_f16(Bt[n][k], At[m][k], acc[ai][bj][m][n], 0, 0, 0); __builtin_amdgcn_s_setprio(0); } while (0)
; #define PG8_WAIT_V(n) asm volatile("s_waitcnt vmcnt(" #n ")" ::: "memory")
; #define PG8_WAIT_L(n) asm volatile("s_waitcnt lgkmcnt(" #n ")" ::: "memory")
; #define PG8_BAR __builtin_amdgcn_s_barrier()
; #define PG8_SCHED __builtin_amdgcn_sched_barrier(0)
;     __device__ __forceinline__ void operator()(f32x4 (&acc)[2][2][4][2], const Unit& u, int wr, int wc, int fr, int fq) const {
;     ...
;         { const int lane = fr + 16 * fq, cL = u.pn * BM + wc * 32 + (lane < 32 ? lane : 96 + lane);
;           float vg = 0.f, vb = 0.f, vt = 0.f;
;           if (hasln) { vg = *(const GAS float*)(pg + cL); vb = *(const GAS float*)(pb + cL); }
;           if (haszh) vt = *(const GAS float*)(tg + cL);
; template <class Epi>
; __device__ __forceinline__ void gemm_phase(LAS unsigned char* lds, const Gemm g0, const StaticOrder& S, const Epi& E) {
;     ...
;             PG8_LDA(At, 1, 1); PG8_STAGE(PG8_SA(1, 0), a3, voffA);
;             PG8_BAR; PG8_WAIT_L(0); PG8_MMA(1, 0, At, B0); PG8_BAR; PG8_SCHED;
;             PG8_STAGE(PG8_SB(1, 1), b3 + hstep, voffB);
;             PG8_WAIT_V(6); PG8_BAR; PG8_MMA(1, 1, At, B1); PG8_BAR;
;         }
	ds_read_b128 v[146:149], v208 offset:49152
	ds_read_b128 v[150:153], v208 offset:50176
	ds_read_b128 v[154:157], v208 offset:51200
	ds_read_b128 v[162:165], v208 offset:52224
	ds_read_b128 v[170:173], v208 offset:53248
	ds_read_b128 v[184:187], v208 offset:54272
	ds_read_b128 v[188:191], v208 offset:55296
	ds_read_b128 v[192:195], v208 offset:56320
	global_load_lds_dwordx4 v226, s[80:81]
	s_mov_b32 m0, s84
	s_nop 0
	global_load_lds_dwordx4 v228, s[80:81]
	s_barrier
	s_waitcnt lgkmcnt(0)
	v_mfma_f32_16x16x32_f16 v[62:65], v[130:133], v[146:149], v[62:65]
	v_mfma_f32_16x16x32_f16 v[58:61], v[138:141], v[146:149], v[58:61]
	v_mfma_f32_16x16x32_f16 v[46:49], v[130:133], v[154:157], v[46:49]
	v_mfma_f32_16x16x32_f16 v[42:45], v[138:141], v[154:157], v[42:45]
	v_mfma_f32_16x16x32_f16 v[30:33], v[130:133], v[170:173], v[30:33]
	v_mfma_f32_16x16x32_f16 v[26:29], v[138:141], v[170:173], v[26:29]
	v_mfma_f32_16x16x32_f16 v[14:17], v[130:133], v[188:191], v[14:17]
	v_mfma_f32_16x16x32_f16 v[10:13], v[138:141], v[188:191], v[10:13]
	v_mfma_f32_16x16x32_f16 v[62:65], v[134:137], v[150:153], v[62:65]
	v_mfma_f32_16x16x32_f16 v[58:61], v[142:145], v[150:153], v[58:61]
	v_mfma_f32_16x16x32_f16 v[46:49], v[134:137], v[162:165], v[46:49]
	v_mfma_f32_16x16x32_f16 v[42:45], v[142:145], v[162:165], v[42:45]
	v_mfma_f32_16x16x32_f16 v[30:33], v[134:137], v[184:187], v[30:33]
	v_mfma_f32_16x16x32_f16 v[26:29], v[142:145], v[184:187], v[26:29]
	v_mfma_f32_16x16x32_f16 v[14:17], v[134:137], v[192:195], v[14:17]
	v_mfma_f32_16x16x32_f16 v[10:13], v[142:145], v[192:195], v[10:13]
	s_barrier
	s_add_u32 s12, s62, 0x160080
	s_addc_u32 s13, s63, 0
	s_add_i32 s23, s90, s19
	s_mov_b32 m0, s23
	s_nop 0
	global_load_lds_dwordx4 v174, s[12:13]
	s_add_i32 m0, s23, 0x2000
	s_nop 0
	global_load_lds_dwordx4 v158, s[12:13]
	s_waitcnt vmcnt(6)
	s_barrier
	v_mfma_f32_16x16x32_f16 v[54:57], v[196:199], v[146:149], v[54:57]
	v_mfma_f32_16x16x32_f16 v[50:53], v[214:217], v[146:149], v[50:53]
	v_mfma_f32_16x16x32_f16 v[38:41], v[196:199], v[154:157], v[38:41]
	v_mfma_f32_16x16x32_f16 v[34:37], v[214:217], v[154:157], v[34:37]
	v_mfma_f32_16x16x32_f16 v[22:25], v[196:199], v[170:173], v[22:25]
	v_mfma_f32_16x16x32_f16 v[18:21], v[214:217], v[170:173], v[18:21]
	v_mfma_f32_16x16x32_f16 v[6:9], v[196:199], v[188:191], v[6:9]
	v_mfma_f32_16x16x32_f16 v[2:5], v[214:217], v[188:191], v[2:5]
	v_mfma_f32_16x16x32_f16 v[54:57], v[210:213], v[150:153], v[54:57]
	v_mfma_f32_16x16x32_f16 v[50:53], v[222:225], v[150:153], v[50:53]
	v_mfma_f32_16x16x32_f16 v[38:41], v[210:213], v[162:165], v[38:41]
	v_mfma_f32_16x16x32_f16 v[34:37], v[222:225], v[162:165], v[34:37]
	v_mfma_f32_16x16x32_f16 v[22:25], v[210:213], v[184:187], v[22:25]
	v_mfma_f32_16x16x32_f16 v[18:21], v[222:225], v[184:187], v[18:21]
	v_mfma_f32_16x16x32_f16 v[6:9], v[210:213], v[192:195], v[6:9]
	v_mfma_f32_16x16x32_f16 v[2:5], v[222:225], v[192:195], v[2:5]
	s_add_i32 s22, s22, 2
	s_add_u32 s24, s24, 0x100
	s_addc_u32 s25, s25, 0
	s_cmpk_gt_u32 s22, 0x55
	s_mov_b64 s[12:13], s[10:11]
	s_barrier
	s_cbranch_scc0 .LBB0_672
	s_lshl_b32 s10, s92, 8
	s_or_b32 s12, s10, s82
	v_add_u32_e32 v130, s12, v204
	v_ashrrev_i32_e32 v131, 31, v130
	v_lshlrev_b64 v[132:133], 2, v[130:131]
	v_lshl_add_u64 v[134:135], s[38:39], 0, v[132:133]
	v_lshl_add_u64 v[132:133], s[48:49], 0, v[132:133]
	global_load_dword v146, v[134:135], off
	global_load_dword v147, v[132:133], off
	v_readlane_b32 s22, v254, 55
	v_readlane_b32 s23, v254, 56
	s_andn2_b64 vcc, exec, s[22:23]
	v_mov_b32_e32 v148, 0
	v_cndmask_b32_e64 v132, 0, 1, s[22:23]
	v_cmp_ne_u32_e64 s[10:11], 1, v132
	s_cbranch_vccnz .LBB0_675
	v_lshl_add_u64 v[130:131], v[130:131], 2, s[50:51]
	global_load_dword v148, v[130:131], off
